# s7 + tail0 layer-1 in_proj blocks dealt interleaved (even/odd) across the 64 workgroups for wider DRAM channel spread
# speedup vs baseline: 1.0030x; 1.0030x over previous
; #define LAS __attribute__((address_space(3)))
; __device__ __forceinline__ float bflo(unsigned w) { return __uint_as_float(w << 16); }
; __device__ __forceinline__ float bfhi(unsigned w) { return __uint_as_float(w & 0xffff0000u); }
; __device__ __forceinline__ void direct_w8_block(const Ctx& c, LAS unsigned char* lds, const float* Wsrc, const int INC_, int srccol, unsigned char* dstrow, float* swdst) {
;     ...
;     f32x4 sc, inv;
; #pragma unroll
;     for (int j = 0; j < 4; ++j) { sc[j] = cm[j] > 0.f ? cm[j] * (1.0f / 127.0f) : 1.0f; inv[j] = 1.0f / sc[j]; }
;     if (wave == 0 && kr == 0) *(f32x4*)(swdst + 4 * nc) = sc;
;     unsigned char* dst = dstrow + (size_t)(4 * nc) * DM + 512 * wave + 8 * kr;
; #pragma unroll
;     for (int t = 0; t < 8; ++t) { unsigned char* dt = dst + t * 64; asm volatile("" : "+v"(dt));
; #pragma unroll
;         for (int j = 0; j < 4; ++j) { v4u pk;
;             if (t < 4) { pk.x = held[t & 3][j][0]; pk.y = held[t & 3][j][1]; pk.z = held[t & 3][j][2]; pk.w = held[t & 3][j][3]; }
;             else pk = *(const LAS v4u*)(hl + ((t - 4) * 4 + j) * 1024);
;             int qi[8];
; #pragma unroll
;             for (int pr = 0; pr < 4; ++pr) { qi[2 * pr] = __float2int_rn(bflo(pk[pr]) * inv[j]); qi[2 * pr + 1] = __float2int_rn(bfhi(pk[pr]) * inv[j]); }
;             v2u w; w.x = (unsigned)(qi[0] & 255) | ((unsigned)(qi[1] & 255) << 8) | ((unsigned)(qi[2] & 255) << 16) | ((unsigned)(qi[3] & 255) << 24);
;             w.y = (unsigned)(qi[4] & 255) | ((unsigned)(qi[5] & 255) << 8) | ((unsigned)(qi[6] & 255) << 16) | ((unsigned)(qi[7] & 255) << 24);
;             *(v2u*)(dt + (size_t)j * DM) = w; } }
; __device__ __forceinline__ void phase_tail_transposes(LAS unsigned char* lds, int part, int wv) {
;     ...
;         if (c.vcu < 192) return;
;         bf16_tiles(c, 0, 7168, 11264, (c.vcu - 192) * NWAVES + c.wave, 64 * NWAVES);
;         for (int cb = c.vcu - 192; cb < NT0; cb += 64) direct_win_block(c, lds, 1, cb);
.LBB0_450:
	s_cmpk_lt_i32 s0, 0xc0
	s_cbranch_scc1 .LBB0_457
	s_cmpk_gt_i32 s0, 0x13f
	s_cbranch_scc1 .LBB0_457
	s_load_dwordx2 s[2:3], s[14:15], 0x30
	v_readlane_b32 s8, v254, 13
	v_lshlrev_b32_e32 v96, 2, v33
	v_readlane_b32 s1, v254, 12
	v_or_b32_e32 v2, s8, v32
	s_waitcnt lgkmcnt(0)
	v_mov_b64_e32 v[0:1], s[2:3]
	v_mad_u64_u32 v[0:1], s[2:3], v2, s61, v[0:1]
	v_lshl_add_u64 v[0:1], v[0:1], 0, v[96:97]
	s_mov_b64 s[2:3], 0x18000000
	v_lshl_add_u64 v[162:163], v[0:1], 0, s[2:3]
	v_readlane_b32 s2, v254, 4
	v_lshlrev_b32_e32 v3, 4, v168
	v_cmp_gt_u32_e64 s[6:7], 8, v168
	v_add_u32_e32 v168, s1, v96
	s_add_i32 s1, 0, 0x20800
	v_readlane_b32 s3, v254, 5
	v_add_u32_e32 v169, s1, v96
	s_and_b64 s[4:5], s[2:3], s[6:7]
	v_lshl_add_u64 v[0:1], s[10:11], 0, v[96:97]
	s_mov_b64 s[2:3], 0x6ff11000
	v_lshlrev_b32_e32 v96, 12, v33
	v_readlane_b32 s9, v254, 14
	v_lshl_add_u64 v[164:165], v[0:1], 0, s[2:3]
	v_lshl_add_u64 v[0:1], s[10:11], 0, v[96:97]
	v_lshl_add_u64 v[0:1], v[0:1], 0, s[8:9]
	v_mov_b32_e32 v33, v97
	v_lshl_add_u64 v[0:1], v[0:1], 0, v[32:33]
	s_mov_b64 s[2:3], 0x6b800000
	s_add_i32 s1, s0, 0xffffff00
	s_lshl_b32 s0, s0, 6
	v_lshl_add_u64 v[166:167], v[0:1], 0, s[2:3]
	s_add_i32 s10, s0, 0xffffd000
	v_add_u32_e32 v96, s52, v3
	s_mov_b32 s0, 0x48000
	s_branch .LBB0_453
.LBB0_452:
	s_or_b64 exec, exec, s[8:9]
	v_div_scale_f32 v134, s[2:3], v130, v130, 1.0
	v_rcp_f32_e32 v135, v134
	v_cvt_pk_bf16_f32 v4, v0, v4
	v_cvt_pk_bf16_f32 v8, v8, v12
	v_lshlrev_b32_e32 v12, 16, v4
	v_fma_f32 v136, -v134, v135, 1.0
	v_fmac_f32_e32 v135, v136, v135
	v_div_scale_f32 v136, vcc, 1.0, v130, 1.0
	v_mul_f32_e32 v137, v136, v135
	v_fma_f32 v138, -v134, v137, v136
	v_fmac_f32_e32 v137, v138, v135
	v_fma_f32 v134, -v134, v137, v136
	v_div_fmas_f32 v134, v134, v135, v137
	v_div_fixup_f32 v135, v134, v130, 1.0
	v_div_scale_f32 v130, s[2:3], v131, v131, 1.0
	v_rcp_f32_e32 v134, v130
	v_and_b32_e32 v4, 0xffff0000, v4
	v_cvt_pk_bf16_f32 v11, v11, v15
	v_cvt_pk_bf16_f32 v15, v3, v7
	v_fma_f32 v136, -v130, v134, 1.0
	v_fmac_f32_e32 v134, v136, v134
	v_div_scale_f32 v136, vcc, 1.0, v131, 1.0
	v_mul_f32_e32 v137, v136, v134
	v_fma_f32 v138, -v130, v137, v136
	v_fmac_f32_e32 v137, v138, v134
	v_fma_f32 v130, -v130, v137, v136
	v_div_fmas_f32 v130, v130, v134, v137
	v_div_fixup_f32 v134, v130, v131, 1.0
	v_div_scale_f32 v130, s[2:3], v132, v132, 1.0
	v_rcp_f32_e32 v131, v130
	v_cvt_pk_bf16_f32 v7, v17, v21
	v_cvt_pk_bf16_f32 v16, v16, v20
	v_mul_f32_e32 v4, v135, v4
	v_fma_f32 v136, -v130, v131, 1.0
	v_lshlrev_b32_e32 v17, 16, v8
	v_and_b32_e32 v8, 0xffff0000, v8
	v_fmac_f32_e32 v131, v136, v131
	v_div_scale_f32 v136, vcc, 1.0, v132, 1.0
	v_cvt_pk_bf16_f32 v9, v9, v13
	v_cvt_pk_bf16_f32 v13, v1, v5
	v_cvt_pk_bf16_f32 v5, v24, v28
	v_mul_f32_e32 v12, v135, v12
	v_rndne_f32_e32 v4, v4
	v_mul_f32_e32 v17, v135, v17
	v_mul_f32_e32 v8, v135, v8
	v_lshlrev_b32_e32 v20, 16, v16
	v_and_b32_e32 v16, 0xffff0000, v16
	v_mul_f32_e32 v137, v136, v131
	v_rndne_f32_e32 v12, v12
	v_cvt_i32_f32_e32 v4, v4
	v_rndne_f32_e32 v17, v17
	v_rndne_f32_e32 v8, v8
	v_mul_f32_e32 v16, v135, v16
	v_lshlrev_b32_e32 v21, 16, v5
	v_and_b32_e32 v5, 0xffff0000, v5
	v_fma_f32 v138, -v130, v137, v136
	v_cvt_i32_f32_e32 v12, v12
	v_cvt_i32_f32_sdwa v17, v17 dst_sel:WORD_1 dst_unused:UNUSED_PAD src0_sel:DWORD
	v_cvt_i32_f32_e32 v8, v8
	v_mul_f32_e32 v20, v135, v20
	v_rndne_f32_e32 v16, v16
	v_mul_f32_e32 v21, v135, v21
	v_mul_f32_e32 v5, v135, v5
	v_fmac_f32_e32 v137, v138, v131
	v_rndne_f32_e32 v20, v20
	v_cvt_i32_f32_e32 v16, v16
	v_rndne_f32_e32 v21, v21
	v_rndne_f32_e32 v5, v5
	v_fma_f32 v130, -v130, v137, v136
	v_cvt_i32_f32_e32 v20, v20
	v_cvt_i32_f32_sdwa v21, v21 dst_sel:WORD_1 dst_unused:UNUSED_PAD src0_sel:DWORD
	v_cvt_i32_f32_e32 v5, v5
	v_div_fmas_f32 v130, v130, v131, v137
	v_lshlrev_b32_e32 v4, 8, v4
	v_div_fixup_f32 v131, v130, v132, 1.0
	v_div_scale_f32 v130, s[2:3], v133, v133, 1.0
	v_and_b32_e32 v4, 0xff00, v4
	v_and_b32_e32 v17, 0xff0000, v17
	v_perm_b32 v8, v8, v12, s81
	s_lshl_b64 s[2:3], s[10:11], 12
	v_or3_b32 v4, v8, v4, v17
	v_lshlrev_b32_e32 v8, 8, v16
	v_lshl_add_u64 v[0:1], v[166:167], 0, s[2:3]
	v_and_b32_e32 v8, 0xff00, v8
	v_and_b32_e32 v12, 0xff0000, v21
	v_perm_b32 v5, v5, v20, s81
	v_cvt_pk_bf16_f32 v10, v10, v14
	v_cvt_pk_bf16_f32 v14, v2, v6
	v_mov_b64_e32 v[2:3], v[0:1]
	v_or3_b32 v5, v5, v8, v12
	global_store_dwordx2 v[2:3], v[4:5], off
	v_and_b32_e32 v5, 0xffff0000, v13
	v_rcp_f32_e32 v132, v130
	v_lshlrev_b32_e32 v4, 16, v13
	v_mul_f32_e32 v5, v134, v5
	v_lshlrev_b32_e32 v8, 16, v9
	v_and_b32_e32 v9, 0xffff0000, v9
	v_cvt_pk_bf16_f32 v6, v25, v29
	v_mul_f32_e32 v4, v134, v4
	v_rndne_f32_e32 v5, v5
	v_mul_f32_e32 v8, v134, v8
	v_mul_f32_e32 v9, v134, v9
	v_lshlrev_b32_e32 v12, 16, v7
	v_and_b32_e32 v7, 0xffff0000, v7
	v_rndne_f32_e32 v4, v4
	v_cvt_i32_f32_e32 v5, v5
	v_rndne_f32_e32 v8, v8
	v_rndne_f32_e32 v9, v9
	v_mul_f32_e32 v7, v134, v7
	v_lshlrev_b32_e32 v13, 16, v6
	v_and_b32_e32 v6, 0xffff0000, v6
	v_cvt_i32_f32_e32 v4, v4
	v_cvt_i32_f32_sdwa v8, v8 dst_sel:WORD_1 dst_unused:UNUSED_PAD src0_sel:DWORD
	v_cvt_i32_f32_e32 v9, v9
	v_mul_f32_e32 v12, v134, v12
	v_rndne_f32_e32 v7, v7
	v_mul_f32_e32 v13, v134, v13
	v_mul_f32_e32 v6, v134, v6
	v_fma_f32 v136, -v130, v132, 1.0
	v_rndne_f32_e32 v12, v12
	v_cvt_i32_f32_e32 v7, v7
	v_rndne_f32_e32 v13, v13
	v_rndne_f32_e32 v6, v6
	v_fmac_f32_e32 v132, v136, v132
	v_div_scale_f32 v136, vcc, 1.0, v133, 1.0
	v_cvt_i32_f32_e32 v12, v12
	v_cvt_i32_f32_sdwa v13, v13 dst_sel:WORD_1 dst_unused:UNUSED_PAD src0_sel:DWORD
	v_cvt_i32_f32_e32 v6, v6
	v_mul_f32_e32 v137, v136, v132
	v_lshlrev_b32_e32 v5, 8, v5
	v_fma_f32 v138, -v130, v137, v136
; #define LAS __attribute__((address_space(3)))
; __device__ __forceinline__ float bflo(unsigned w) { return __uint_as_float(w << 16); }
; __device__ __forceinline__ float bfhi(unsigned w) { return __uint_as_float(w & 0xffff0000u); }
; __device__ __forceinline__ void direct_w8_block(const Ctx& c, LAS unsigned char* lds, const float* Wsrc, const int INC_, int srccol, unsigned char* dstrow, float* swdst) {
;     ...
; #pragma unroll
;     for (int t = 0; t < 8; ++t) { unsigned char* dt = dst + t * 64; asm volatile("" : "+v"(dt));
; #pragma unroll
;         for (int j = 0; j < 4; ++j) { v4u pk;
;             if (t < 4) { pk.x = held[t & 3][j][0]; pk.y = held[t & 3][j][1]; pk.z = held[t & 3][j][2]; pk.w = held[t & 3][j][3]; }
;             else pk = *(const LAS v4u*)(hl + ((t - 4) * 4 + j) * 1024);
;             int qi[8];
; #pragma unroll
;             for (int pr = 0; pr < 4; ++pr) { qi[2 * pr] = __float2int_rn(bflo(pk[pr]) * inv[j]); qi[2 * pr + 1] = __float2int_rn(bfhi(pk[pr]) * inv[j]); }
;             v2u w; w.x = (unsigned)(qi[0] & 255) | ((unsigned)(qi[1] & 255) << 8) | ((unsigned)(qi[2] & 255) << 16) | ((unsigned)(qi[3] & 255) << 24);
;             w.y = (unsigned)(qi[4] & 255) | ((unsigned)(qi[5] & 255) << 8) | ((unsigned)(qi[6] & 255) << 16) | ((unsigned)(qi[7] & 255) << 24);
;             *(v2u*)(dt + (size_t)j * DM) = w; } }
	v_and_b32_e32 v5, 0xff00, v5
	v_and_b32_e32 v8, 0xff0000, v8
	v_perm_b32 v4, v9, v4, s81
	v_fmac_f32_e32 v137, v138, v132
	v_or3_b32 v4, v4, v5, v8
	v_lshlrev_b32_e32 v5, 8, v7
	v_fma_f32 v130, -v130, v137, v136
	v_and_b32_e32 v5, 0xff00, v5
	v_and_b32_e32 v7, 0xff0000, v13
	v_perm_b32 v6, v6, v12, s81
	v_div_fmas_f32 v130, v130, v132, v137
	v_or3_b32 v5, v6, v5, v7
	v_add_co_u32_e32 v6, vcc, s67, v2
	v_cvt_pk_bf16_f32 v18, v18, v22
	s_nop 0
	v_addc_co_u32_e32 v7, vcc, 0, v3, vcc
	global_store_dwordx2 v[6:7], v[4:5], off
	v_and_b32_e32 v5, 0xffff0000, v14
	v_lshlrev_b32_e32 v4, 16, v14
	v_mul_f32_e32 v5, v131, v5
	v_lshlrev_b32_e32 v6, 16, v10
	v_and_b32_e32 v7, 0xffff0000, v10
	v_cvt_pk_bf16_f32 v19, v19, v23
	v_cvt_pk_bf16_f32 v23, v26, v30
	v_mul_f32_e32 v4, v131, v4
	v_rndne_f32_e32 v5, v5
	v_mul_f32_e32 v6, v131, v6
	v_mul_f32_e32 v7, v131, v7
	v_and_b32_e32 v9, 0xffff0000, v18
	v_rndne_f32_e32 v4, v4
	v_cvt_i32_f32_e32 v5, v5
	v_rndne_f32_e32 v6, v6
	v_rndne_f32_e32 v7, v7
	v_lshlrev_b32_e32 v8, 16, v18
	v_mul_f32_e32 v9, v131, v9
	v_lshlrev_b32_e32 v10, 16, v23
	v_and_b32_e32 v12, 0xffff0000, v23
	v_cvt_i32_f32_e32 v4, v4
	v_cvt_i32_f32_sdwa v6, v6 dst_sel:WORD_1 dst_unused:UNUSED_PAD src0_sel:DWORD
	v_cvt_i32_f32_e32 v7, v7
	v_mul_f32_e32 v8, v131, v8
	v_rndne_f32_e32 v9, v9
	v_mul_f32_e32 v10, v131, v10
	v_mul_f32_e32 v12, v131, v12
	v_rndne_f32_e32 v8, v8
	v_cvt_i32_f32_e32 v9, v9
	v_rndne_f32_e32 v10, v10
	v_rndne_f32_e32 v12, v12
	v_cvt_i32_f32_e32 v8, v8
	v_cvt_i32_f32_sdwa v10, v10 dst_sel:WORD_1 dst_unused:UNUSED_PAD src0_sel:DWORD
	v_cvt_i32_f32_e32 v12, v12
	v_lshlrev_b32_e32 v5, 8, v5
	v_and_b32_e32 v5, 0xff00, v5
	v_and_b32_e32 v6, 0xff0000, v6
	v_perm_b32 v4, v7, v4, s81
	v_or3_b32 v4, v4, v5, v6
	v_lshlrev_b32_e32 v5, 8, v9
	v_and_b32_e32 v5, 0xff00, v5
	v_and_b32_e32 v6, 0xff0000, v10
	v_perm_b32 v7, v12, v8, s81
	v_or3_b32 v5, v7, v5, v6
	v_add_co_u32_e32 v6, vcc, s33, v2
	v_div_fixup_f32 v130, v130, v133, 1.0
	s_nop 0
	v_addc_co_u32_e32 v7, vcc, 0, v3, vcc
	global_store_dwordx2 v[6:7], v[4:5], off
	v_and_b32_e32 v5, 0xffff0000, v15
	v_lshlrev_b32_e32 v4, 16, v15
	v_mul_f32_e32 v5, v130, v5
	v_lshlrev_b32_e32 v6, 16, v11
	v_and_b32_e32 v7, 0xffff0000, v11
	v_cvt_pk_bf16_f32 v27, v27, v31
	v_mul_f32_e32 v4, v130, v4
	v_rndne_f32_e32 v5, v5
	v_mul_f32_e32 v6, v130, v6
	v_mul_f32_e32 v7, v130, v7
	v_and_b32_e32 v9, 0xffff0000, v19
	v_rndne_f32_e32 v4, v4
	v_cvt_i32_f32_e32 v5, v5
	v_rndne_f32_e32 v6, v6
	v_rndne_f32_e32 v7, v7
	v_lshlrev_b32_e32 v8, 16, v19
	v_mul_f32_e32 v9, v130, v9
	v_lshlrev_b32_e32 v10, 16, v27
	v_and_b32_e32 v11, 0xffff0000, v27
	v_cvt_i32_f32_e32 v4, v4
	v_cvt_i32_f32_sdwa v6, v6 dst_sel:WORD_1 dst_unused:UNUSED_PAD src0_sel:DWORD
	v_cvt_i32_f32_e32 v7, v7
	v_mul_f32_e32 v8, v130, v8
	v_rndne_f32_e32 v9, v9
	v_mul_f32_e32 v10, v130, v10
	v_mul_f32_e32 v11, v130, v11
	v_rndne_f32_e32 v8, v8
	v_cvt_i32_f32_e32 v9, v9
	v_rndne_f32_e32 v10, v10
	v_rndne_f32_e32 v11, v11
	v_cvt_i32_f32_e32 v8, v8
	v_cvt_i32_f32_sdwa v10, v10 dst_sel:WORD_1 dst_unused:UNUSED_PAD src0_sel:DWORD
	v_cvt_i32_f32_e32 v11, v11
	v_lshlrev_b32_e32 v5, 8, v5
	v_and_b32_e32 v5, 0xff00, v5
	v_and_b32_e32 v6, 0xff0000, v6
	v_perm_b32 v4, v7, v4, s81
	v_or3_b32 v4, v4, v5, v6
	v_lshlrev_b32_e32 v5, 8, v9
	v_and_b32_e32 v5, 0xff00, v5
	v_and_b32_e32 v6, 0xff0000, v10
	v_perm_b32 v7, v11, v8, s81
	v_add_co_u32_e32 v2, vcc, s44, v2
	v_cvt_pk_bf16_f32 v32, v32, v36
	v_or3_b32 v5, v7, v5, v6
	v_addc_co_u32_e32 v3, vcc, 0, v3, vcc
	v_cvt_pk_bf16_f32 v40, v40, v44
	global_store_dwordx2 v[2:3], v[4:5], off
	v_and_b32_e32 v5, 0xffff0000, v32
	v_cvt_pk_bf16_f32 v41, v41, v45
	v_cvt_pk_bf16_f32 v45, v48, v52
	v_lshlrev_b32_e32 v4, 16, v32
	v_mul_f32_e32 v5, v135, v5
	v_lshlrev_b32_e32 v6, 16, v40
	v_and_b32_e32 v7, 0xffff0000, v40
	v_cvt_pk_bf16_f32 v33, v33, v37
	v_cvt_pk_bf16_f32 v37, v56, v60
	v_mul_f32_e32 v4, v135, v4
	v_rndne_f32_e32 v5, v5
	v_mul_f32_e32 v6, v135, v6
	v_mul_f32_e32 v7, v135, v7
	v_and_b32_e32 v9, 0xffff0000, v45
	v_rndne_f32_e32 v4, v4
	v_cvt_i32_f32_e32 v5, v5
	v_rndne_f32_e32 v6, v6
	v_rndne_f32_e32 v7, v7
	v_lshlrev_b32_e32 v8, 16, v45
	v_mul_f32_e32 v9, v135, v9
	v_lshlrev_b32_e32 v10, 16, v37
	v_and_b32_e32 v11, 0xffff0000, v37
	v_cvt_i32_f32_e32 v4, v4
	v_cvt_i32_f32_sdwa v6, v6 dst_sel:WORD_1 dst_unused:UNUSED_PAD src0_sel:DWORD
	v_cvt_i32_f32_e32 v7, v7
	v_mul_f32_e32 v8, v135, v8
	v_rndne_f32_e32 v9, v9
	v_mul_f32_e32 v10, v135, v10
	v_mul_f32_e32 v11, v135, v11
	v_rndne_f32_e32 v8, v8
	v_cvt_i32_f32_e32 v9, v9
	v_rndne_f32_e32 v10, v10
	v_rndne_f32_e32 v11, v11
	v_cvt_i32_f32_e32 v8, v8
	v_cvt_i32_f32_sdwa v10, v10 dst_sel:WORD_1 dst_unused:UNUSED_PAD src0_sel:DWORD
	v_cvt_i32_f32_e32 v11, v11
	v_lshlrev_b32_e32 v5, 8, v5
	v_and_b32_e32 v5, 0xff00, v5
	v_and_b32_e32 v6, 0xff0000, v6
	v_perm_b32 v4, v7, v4, s81
	v_or3_b32 v4, v4, v5, v6
	v_lshlrev_b32_e32 v5, 8, v9
	v_and_b32_e32 v5, 0xff00, v5
	v_and_b32_e32 v6, 0xff0000, v10
	v_perm_b32 v7, v11, v8, s81
	v_lshl_add_u64 v[2:3], v[0:1], 0, 64
	v_or3_b32 v5, v7, v5, v6
	global_store_dwordx2 v[2:3], v[4:5], off
	v_and_b32_e32 v5, 0xffff0000, v33
	v_cvt_pk_bf16_f32 v42, v42, v46
	v_cvt_pk_bf16_f32 v46, v49, v53
	v_lshlrev_b32_e32 v4, 16, v33
	v_mul_f32_e32 v5, v134, v5
	v_lshlrev_b32_e32 v6, 16, v41
	v_and_b32_e32 v7, 0xffff0000, v41
	v_cvt_pk_bf16_f32 v34, v34, v38
	v_cvt_pk_bf16_f32 v38, v57, v61
	v_mul_f32_e32 v4, v134, v4
	v_rndne_f32_e32 v5, v5
	v_mul_f32_e32 v6, v134, v6
	v_mul_f32_e32 v7, v134, v7
	v_and_b32_e32 v9, 0xffff0000, v46
	v_rndne_f32_e32 v4, v4
	v_cvt_i32_f32_e32 v5, v5
	v_rndne_f32_e32 v6, v6
	v_rndne_f32_e32 v7, v7
	v_lshlrev_b32_e32 v8, 16, v46
; #define LAS __attribute__((address_space(3)))
; __device__ __forceinline__ float bflo(unsigned w) { return __uint_as_float(w << 16); }
; __device__ __forceinline__ float bfhi(unsigned w) { return __uint_as_float(w & 0xffff0000u); }
; __device__ __forceinline__ void direct_w8_block(const Ctx& c, LAS unsigned char* lds, const float* Wsrc, const int INC_, int srccol, unsigned char* dstrow, float* swdst) {
;     ...
; #pragma unroll
;     for (int t = 0; t < 8; ++t) { unsigned char* dt = dst + t * 64; asm volatile("" : "+v"(dt));
; #pragma unroll
;         for (int j = 0; j < 4; ++j) { v4u pk;
;             if (t < 4) { pk.x = held[t & 3][j][0]; pk.y = held[t & 3][j][1]; pk.z = held[t & 3][j][2]; pk.w = held[t & 3][j][3]; }
;             else pk = *(const LAS v4u*)(hl + ((t - 4) * 4 + j) * 1024);
;             int qi[8];
; #pragma unroll
;             for (int pr = 0; pr < 4; ++pr) { qi[2 * pr] = __float2int_rn(bflo(pk[pr]) * inv[j]); qi[2 * pr + 1] = __float2int_rn(bfhi(pk[pr]) * inv[j]); }
;             v2u w; w.x = (unsigned)(qi[0] & 255) | ((unsigned)(qi[1] & 255) << 8) | ((unsigned)(qi[2] & 255) << 16) | ((unsigned)(qi[3] & 255) << 24);
;             w.y = (unsigned)(qi[4] & 255) | ((unsigned)(qi[5] & 255) << 8) | ((unsigned)(qi[6] & 255) << 16) | ((unsigned)(qi[7] & 255) << 24);
;             *(v2u*)(dt + (size_t)j * DM) = w; } }
	v_mul_f32_e32 v9, v134, v9
	v_lshlrev_b32_e32 v10, 16, v38
	v_and_b32_e32 v11, 0xffff0000, v38
	v_cvt_i32_f32_e32 v4, v4
	v_cvt_i32_f32_sdwa v6, v6 dst_sel:WORD_1 dst_unused:UNUSED_PAD src0_sel:DWORD
	v_cvt_i32_f32_e32 v7, v7
	v_mul_f32_e32 v8, v134, v8
	v_rndne_f32_e32 v9, v9
	v_mul_f32_e32 v10, v134, v10
	v_mul_f32_e32 v11, v134, v11
	v_rndne_f32_e32 v8, v8
	v_cvt_i32_f32_e32 v9, v9
	v_rndne_f32_e32 v10, v10
	v_rndne_f32_e32 v11, v11
	v_cvt_i32_f32_e32 v8, v8
	v_cvt_i32_f32_sdwa v10, v10 dst_sel:WORD_1 dst_unused:UNUSED_PAD src0_sel:DWORD
	v_cvt_i32_f32_e32 v11, v11
	v_lshlrev_b32_e32 v5, 8, v5
	v_and_b32_e32 v5, 0xff00, v5
	v_and_b32_e32 v6, 0xff0000, v6
	v_perm_b32 v4, v7, v4, s81
	v_or3_b32 v4, v4, v5, v6
	v_lshlrev_b32_e32 v5, 8, v9
	v_and_b32_e32 v5, 0xff00, v5
	v_and_b32_e32 v6, 0xff0000, v10
	v_perm_b32 v7, v11, v8, s81
	v_or3_b32 v5, v7, v5, v6
	v_add_co_u32_e32 v6, vcc, s67, v2
	v_cvt_pk_bf16_f32 v43, v43, v47
	s_nop 0
	v_addc_co_u32_e32 v7, vcc, 0, v3, vcc
	global_store_dwordx2 v[6:7], v[4:5], off
	v_and_b32_e32 v5, 0xffff0000, v34
	v_cvt_pk_bf16_f32 v47, v50, v54
	v_lshlrev_b32_e32 v4, 16, v34
	v_mul_f32_e32 v5, v131, v5
	v_lshlrev_b32_e32 v6, 16, v42
	v_and_b32_e32 v7, 0xffff0000, v42
	v_cvt_pk_bf16_f32 v35, v35, v39
	v_cvt_pk_bf16_f32 v39, v58, v62
	v_mul_f32_e32 v4, v131, v4
	v_rndne_f32_e32 v5, v5
	v_mul_f32_e32 v6, v131, v6
	v_mul_f32_e32 v7, v131, v7
	v_and_b32_e32 v9, 0xffff0000, v47
	v_rndne_f32_e32 v4, v4
	v_cvt_i32_f32_e32 v5, v5
	v_rndne_f32_e32 v6, v6
	v_rndne_f32_e32 v7, v7
	v_lshlrev_b32_e32 v8, 16, v47
	v_mul_f32_e32 v9, v131, v9
	v_lshlrev_b32_e32 v10, 16, v39
	v_and_b32_e32 v11, 0xffff0000, v39
	v_cvt_i32_f32_e32 v4, v4
	v_cvt_i32_f32_sdwa v6, v6 dst_sel:WORD_1 dst_unused:UNUSED_PAD src0_sel:DWORD
	v_cvt_i32_f32_e32 v7, v7
	v_mul_f32_e32 v8, v131, v8
	v_rndne_f32_e32 v9, v9
	v_mul_f32_e32 v10, v131, v10
	v_mul_f32_e32 v11, v131, v11
	v_rndne_f32_e32 v8, v8
	v_cvt_i32_f32_e32 v9, v9
	v_rndne_f32_e32 v10, v10
	v_rndne_f32_e32 v11, v11
	v_cvt_i32_f32_e32 v8, v8
	v_cvt_i32_f32_sdwa v10, v10 dst_sel:WORD_1 dst_unused:UNUSED_PAD src0_sel:DWORD
	v_cvt_i32_f32_e32 v11, v11
	v_lshlrev_b32_e32 v5, 8, v5
	v_and_b32_e32 v5, 0xff00, v5
	v_and_b32_e32 v6, 0xff0000, v6
	v_perm_b32 v4, v7, v4, s81
	v_or3_b32 v4, v4, v5, v6
	v_lshlrev_b32_e32 v5, 8, v9
	v_and_b32_e32 v5, 0xff00, v5
	v_and_b32_e32 v6, 0xff0000, v10
	v_perm_b32 v7, v11, v8, s81
	v_or3_b32 v5, v7, v5, v6
	v_add_co_u32_e32 v6, vcc, s33, v2
	v_cvt_pk_bf16_f32 v51, v51, v55
	s_nop 0
	v_addc_co_u32_e32 v7, vcc, 0, v3, vcc
	global_store_dwordx2 v[6:7], v[4:5], off
	v_and_b32_e32 v5, 0xffff0000, v35
	v_lshlrev_b32_e32 v4, 16, v35
	v_mul_f32_e32 v5, v130, v5
	v_lshlrev_b32_e32 v6, 16, v43
	v_and_b32_e32 v7, 0xffff0000, v43
	v_cvt_pk_bf16_f32 v59, v59, v63
	v_mul_f32_e32 v4, v130, v4
	v_rndne_f32_e32 v5, v5
	v_mul_f32_e32 v6, v130, v6
	v_mul_f32_e32 v7, v130, v7
	v_and_b32_e32 v9, 0xffff0000, v51
	v_rndne_f32_e32 v4, v4
	v_cvt_i32_f32_e32 v5, v5
	v_rndne_f32_e32 v6, v6
	v_rndne_f32_e32 v7, v7
	v_lshlrev_b32_e32 v8, 16, v51
	v_mul_f32_e32 v9, v130, v9
	v_lshlrev_b32_e32 v10, 16, v59
	v_and_b32_e32 v11, 0xffff0000, v59
	v_cvt_i32_f32_e32 v4, v4
	v_cvt_i32_f32_sdwa v6, v6 dst_sel:WORD_1 dst_unused:UNUSED_PAD src0_sel:DWORD
	v_cvt_i32_f32_e32 v7, v7
	v_mul_f32_e32 v8, v130, v8
	v_rndne_f32_e32 v9, v9
	v_mul_f32_e32 v10, v130, v10
	v_mul_f32_e32 v11, v130, v11
	v_rndne_f32_e32 v8, v8
	v_cvt_i32_f32_e32 v9, v9
	v_rndne_f32_e32 v10, v10
	v_rndne_f32_e32 v11, v11
	v_cvt_i32_f32_e32 v8, v8
	v_cvt_i32_f32_sdwa v10, v10 dst_sel:WORD_1 dst_unused:UNUSED_PAD src0_sel:DWORD
	v_cvt_i32_f32_e32 v11, v11
	v_lshlrev_b32_e32 v5, 8, v5
	v_and_b32_e32 v5, 0xff00, v5
	v_and_b32_e32 v6, 0xff0000, v6
	v_perm_b32 v4, v7, v4, s81
	v_or3_b32 v4, v4, v5, v6
	v_lshlrev_b32_e32 v5, 8, v9
	v_and_b32_e32 v5, 0xff00, v5
	v_and_b32_e32 v6, 0xff0000, v10
	v_perm_b32 v7, v11, v8, s81
	v_add_co_u32_e32 v2, vcc, s44, v2
	v_cvt_pk_bf16_f32 v64, v64, v68
	v_or3_b32 v5, v7, v5, v6
	v_addc_co_u32_e32 v3, vcc, 0, v3, vcc
	v_cvt_pk_bf16_f32 v72, v72, v76
	global_store_dwordx2 v[2:3], v[4:5], off
	v_and_b32_e32 v5, 0xffff0000, v64
	v_cvt_pk_bf16_f32 v73, v73, v77
	v_cvt_pk_bf16_f32 v77, v80, v84
	v_lshlrev_b32_e32 v4, 16, v64
	v_mul_f32_e32 v5, v135, v5
	v_lshlrev_b32_e32 v6, 16, v72
	v_and_b32_e32 v7, 0xffff0000, v72
	v_cvt_pk_bf16_f32 v65, v65, v69
	v_cvt_pk_bf16_f32 v69, v88, v92
	v_mul_f32_e32 v4, v135, v4
	v_rndne_f32_e32 v5, v5
	v_mul_f32_e32 v6, v135, v6
	v_mul_f32_e32 v7, v135, v7
	v_and_b32_e32 v9, 0xffff0000, v77
	v_rndne_f32_e32 v4, v4
	v_cvt_i32_f32_e32 v5, v5
	v_rndne_f32_e32 v6, v6
	v_rndne_f32_e32 v7, v7
	v_lshlrev_b32_e32 v8, 16, v77
	v_mul_f32_e32 v9, v135, v9
	v_lshlrev_b32_e32 v10, 16, v69
	v_and_b32_e32 v11, 0xffff0000, v69
	v_cvt_i32_f32_e32 v4, v4
	v_cvt_i32_f32_sdwa v6, v6 dst_sel:WORD_1 dst_unused:UNUSED_PAD src0_sel:DWORD
	v_cvt_i32_f32_e32 v7, v7
	v_mul_f32_e32 v8, v135, v8
	v_rndne_f32_e32 v9, v9
	v_mul_f32_e32 v10, v135, v10
	v_mul_f32_e32 v11, v135, v11
	v_rndne_f32_e32 v8, v8
	v_cvt_i32_f32_e32 v9, v9
	v_rndne_f32_e32 v10, v10
	v_rndne_f32_e32 v11, v11
	v_cvt_i32_f32_e32 v8, v8
	v_cvt_i32_f32_sdwa v10, v10 dst_sel:WORD_1 dst_unused:UNUSED_PAD src0_sel:DWORD
	v_cvt_i32_f32_e32 v11, v11
	v_lshlrev_b32_e32 v5, 8, v5
	v_and_b32_e32 v5, 0xff00, v5
	v_and_b32_e32 v6, 0xff0000, v6
	v_perm_b32 v4, v7, v4, s81
	v_or3_b32 v4, v4, v5, v6
	v_lshlrev_b32_e32 v5, 8, v9
	v_and_b32_e32 v5, 0xff00, v5
	v_and_b32_e32 v6, 0xff0000, v10
	v_perm_b32 v7, v11, v8, s81
	v_lshl_add_u64 v[2:3], v[0:1], 0, s[42:43]
	v_or3_b32 v5, v7, v5, v6
	global_store_dwordx2 v[2:3], v[4:5], off
	v_and_b32_e32 v5, 0xffff0000, v65
; #define LAS __attribute__((address_space(3)))
; __device__ __forceinline__ float bflo(unsigned w) { return __uint_as_float(w << 16); }
; __device__ __forceinline__ float bfhi(unsigned w) { return __uint_as_float(w & 0xffff0000u); }
; __device__ __forceinline__ void direct_w8_block(const Ctx& c, LAS unsigned char* lds, const float* Wsrc, const int INC_, int srccol, unsigned char* dstrow, float* swdst) {
;     ...
; #pragma unroll
;     for (int t = 0; t < 8; ++t) { unsigned char* dt = dst + t * 64; asm volatile("" : "+v"(dt));
; #pragma unroll
;         for (int j = 0; j < 4; ++j) { v4u pk;
;             if (t < 4) { pk.x = held[t & 3][j][0]; pk.y = held[t & 3][j][1]; pk.z = held[t & 3][j][2]; pk.w = held[t & 3][j][3]; }
;             else pk = *(const LAS v4u*)(hl + ((t - 4) * 4 + j) * 1024);
;             int qi[8];
; #pragma unroll
;             for (int pr = 0; pr < 4; ++pr) { qi[2 * pr] = __float2int_rn(bflo(pk[pr]) * inv[j]); qi[2 * pr + 1] = __float2int_rn(bfhi(pk[pr]) * inv[j]); }
;             v2u w; w.x = (unsigned)(qi[0] & 255) | ((unsigned)(qi[1] & 255) << 8) | ((unsigned)(qi[2] & 255) << 16) | ((unsigned)(qi[3] & 255) << 24);
;             w.y = (unsigned)(qi[4] & 255) | ((unsigned)(qi[5] & 255) << 8) | ((unsigned)(qi[6] & 255) << 16) | ((unsigned)(qi[7] & 255) << 24);
;             *(v2u*)(dt + (size_t)j * DM) = w; } }
	v_cvt_pk_bf16_f32 v74, v74, v78
	v_cvt_pk_bf16_f32 v78, v81, v85
	v_lshlrev_b32_e32 v4, 16, v65
	v_mul_f32_e32 v5, v134, v5
	v_lshlrev_b32_e32 v6, 16, v73
	v_and_b32_e32 v7, 0xffff0000, v73
	v_cvt_pk_bf16_f32 v66, v66, v70
	v_cvt_pk_bf16_f32 v70, v89, v93
	v_mul_f32_e32 v4, v134, v4
	v_rndne_f32_e32 v5, v5
	v_mul_f32_e32 v6, v134, v6
	v_mul_f32_e32 v7, v134, v7
	v_and_b32_e32 v9, 0xffff0000, v78
	v_rndne_f32_e32 v4, v4
	v_cvt_i32_f32_e32 v5, v5
	v_rndne_f32_e32 v6, v6
	v_rndne_f32_e32 v7, v7
	v_lshlrev_b32_e32 v8, 16, v78
	v_mul_f32_e32 v9, v134, v9
	v_lshlrev_b32_e32 v10, 16, v70
	v_and_b32_e32 v11, 0xffff0000, v70
	v_cvt_i32_f32_e32 v4, v4
	v_cvt_i32_f32_sdwa v6, v6 dst_sel:WORD_1 dst_unused:UNUSED_PAD src0_sel:DWORD
	v_cvt_i32_f32_e32 v7, v7
	v_mul_f32_e32 v8, v134, v8
	v_rndne_f32_e32 v9, v9
	v_mul_f32_e32 v10, v134, v10
	v_mul_f32_e32 v11, v134, v11
	v_rndne_f32_e32 v8, v8
	v_cvt_i32_f32_e32 v9, v9
	v_rndne_f32_e32 v10, v10
	v_rndne_f32_e32 v11, v11
	v_cvt_i32_f32_e32 v8, v8
	v_cvt_i32_f32_sdwa v10, v10 dst_sel:WORD_1 dst_unused:UNUSED_PAD src0_sel:DWORD
	v_cvt_i32_f32_e32 v11, v11
	v_lshlrev_b32_e32 v5, 8, v5
	v_and_b32_e32 v5, 0xff00, v5
	v_and_b32_e32 v6, 0xff0000, v6
	v_perm_b32 v4, v7, v4, s81
	v_or3_b32 v4, v4, v5, v6
	v_lshlrev_b32_e32 v5, 8, v9
	v_and_b32_e32 v5, 0xff00, v5
	v_and_b32_e32 v6, 0xff0000, v10
	v_perm_b32 v7, v11, v8, s81
	v_or3_b32 v5, v7, v5, v6
	v_add_co_u32_e32 v6, vcc, s67, v2
	v_cvt_pk_bf16_f32 v75, v75, v79
	s_nop 0
	v_addc_co_u32_e32 v7, vcc, 0, v3, vcc
	global_store_dwordx2 v[6:7], v[4:5], off
	v_and_b32_e32 v5, 0xffff0000, v66
	v_cvt_pk_bf16_f32 v79, v82, v86
	v_lshlrev_b32_e32 v4, 16, v66
	v_mul_f32_e32 v5, v131, v5
	v_lshlrev_b32_e32 v6, 16, v74
	v_and_b32_e32 v7, 0xffff0000, v74
	v_cvt_pk_bf16_f32 v67, v67, v71
	v_cvt_pk_bf16_f32 v71, v90, v94
	v_mul_f32_e32 v4, v131, v4
	v_rndne_f32_e32 v5, v5
	v_mul_f32_e32 v6, v131, v6
	v_mul_f32_e32 v7, v131, v7
	v_and_b32_e32 v9, 0xffff0000, v79
	v_rndne_f32_e32 v4, v4
	v_cvt_i32_f32_e32 v5, v5
	v_rndne_f32_e32 v6, v6
	v_rndne_f32_e32 v7, v7
	v_lshlrev_b32_e32 v8, 16, v79
	v_mul_f32_e32 v9, v131, v9
	v_lshlrev_b32_e32 v10, 16, v71
	v_and_b32_e32 v11, 0xffff0000, v71
	v_cvt_i32_f32_e32 v4, v4
	v_cvt_i32_f32_sdwa v6, v6 dst_sel:WORD_1 dst_unused:UNUSED_PAD src0_sel:DWORD
	v_cvt_i32_f32_e32 v7, v7
	v_mul_f32_e32 v8, v131, v8
	v_rndne_f32_e32 v9, v9
	v_mul_f32_e32 v10, v131, v10
	v_mul_f32_e32 v11, v131, v11
	v_rndne_f32_e32 v8, v8
	v_cvt_i32_f32_e32 v9, v9
	v_rndne_f32_e32 v10, v10
	v_rndne_f32_e32 v11, v11
	v_cvt_i32_f32_e32 v8, v8
	v_cvt_i32_f32_sdwa v10, v10 dst_sel:WORD_1 dst_unused:UNUSED_PAD src0_sel:DWORD
	v_cvt_i32_f32_e32 v11, v11
	v_lshlrev_b32_e32 v5, 8, v5
	v_and_b32_e32 v5, 0xff00, v5
	v_and_b32_e32 v6, 0xff0000, v6
	v_perm_b32 v4, v7, v4, s81
	v_or3_b32 v4, v4, v5, v6
	v_lshlrev_b32_e32 v5, 8, v9
	v_and_b32_e32 v5, 0xff00, v5
	v_and_b32_e32 v6, 0xff0000, v10
	v_perm_b32 v7, v11, v8, s81
	v_or3_b32 v5, v7, v5, v6
	v_add_co_u32_e32 v6, vcc, s33, v2
	v_cvt_pk_bf16_f32 v83, v83, v87
	s_nop 0
	v_addc_co_u32_e32 v7, vcc, 0, v3, vcc
	global_store_dwordx2 v[6:7], v[4:5], off
	v_and_b32_e32 v5, 0xffff0000, v67
	v_lshlrev_b32_e32 v4, 16, v67
	v_mul_f32_e32 v5, v130, v5
	v_lshlrev_b32_e32 v6, 16, v75
	v_and_b32_e32 v7, 0xffff0000, v75
	v_cvt_pk_bf16_f32 v91, v91, v95
	v_mul_f32_e32 v4, v130, v4
	v_rndne_f32_e32 v5, v5
	v_mul_f32_e32 v6, v130, v6
	v_mul_f32_e32 v7, v130, v7
	v_and_b32_e32 v9, 0xffff0000, v83
	v_rndne_f32_e32 v4, v4
	v_cvt_i32_f32_e32 v5, v5
	v_rndne_f32_e32 v6, v6
	v_rndne_f32_e32 v7, v7
	v_lshlrev_b32_e32 v8, 16, v83
	v_mul_f32_e32 v9, v130, v9
	v_lshlrev_b32_e32 v10, 16, v91
	v_and_b32_e32 v11, 0xffff0000, v91
	v_cvt_i32_f32_e32 v4, v4
	v_cvt_i32_f32_sdwa v6, v6 dst_sel:WORD_1 dst_unused:UNUSED_PAD src0_sel:DWORD
	v_cvt_i32_f32_e32 v7, v7
	v_mul_f32_e32 v8, v130, v8
	v_rndne_f32_e32 v9, v9
	v_mul_f32_e32 v10, v130, v10
	v_mul_f32_e32 v11, v130, v11
	v_rndne_f32_e32 v8, v8
	v_cvt_i32_f32_e32 v9, v9
	v_rndne_f32_e32 v10, v10
	v_rndne_f32_e32 v11, v11
	v_cvt_i32_f32_e32 v8, v8
	v_cvt_i32_f32_sdwa v10, v10 dst_sel:WORD_1 dst_unused:UNUSED_PAD src0_sel:DWORD
	v_cvt_i32_f32_e32 v11, v11
	v_lshlrev_b32_e32 v5, 8, v5
	v_and_b32_e32 v5, 0xff00, v5
	v_and_b32_e32 v6, 0xff0000, v6
	v_perm_b32 v4, v7, v4, s81
	v_or3_b32 v4, v4, v5, v6
	v_lshlrev_b32_e32 v5, 8, v9
	v_and_b32_e32 v5, 0xff00, v5
	v_and_b32_e32 v6, 0xff0000, v10
	v_perm_b32 v7, v11, v8, s81
	v_add_co_u32_e32 v2, vcc, s44, v2
	v_cvt_pk_bf16_f32 v98, v98, v102
	v_or3_b32 v5, v7, v5, v6
	v_addc_co_u32_e32 v3, vcc, 0, v3, vcc
	v_cvt_pk_bf16_f32 v106, v106, v110
	global_store_dwordx2 v[2:3], v[4:5], off
	v_and_b32_e32 v5, 0xffff0000, v98
	v_cvt_pk_bf16_f32 v107, v107, v111
	v_cvt_pk_bf16_f32 v111, v114, v118
	v_lshlrev_b32_e32 v4, 16, v98
	v_mul_f32_e32 v5, v135, v5
	v_lshlrev_b32_e32 v6, 16, v106
	v_and_b32_e32 v7, 0xffff0000, v106
	v_cvt_pk_bf16_f32 v99, v99, v103
	v_cvt_pk_bf16_f32 v103, v122, v126
	v_mul_f32_e32 v4, v135, v4
	v_rndne_f32_e32 v5, v5
	v_mul_f32_e32 v6, v135, v6
	v_mul_f32_e32 v7, v135, v7
	v_and_b32_e32 v9, 0xffff0000, v111
	v_rndne_f32_e32 v4, v4
	v_cvt_i32_f32_e32 v5, v5
	v_rndne_f32_e32 v6, v6
	v_rndne_f32_e32 v7, v7
	v_lshlrev_b32_e32 v8, 16, v111
	v_mul_f32_e32 v9, v135, v9
	v_lshlrev_b32_e32 v10, 16, v103
	v_and_b32_e32 v11, 0xffff0000, v103
	v_cvt_i32_f32_e32 v4, v4
	v_cvt_i32_f32_sdwa v6, v6 dst_sel:WORD_1 dst_unused:UNUSED_PAD src0_sel:DWORD
	v_cvt_i32_f32_e32 v7, v7
	v_mul_f32_e32 v8, v135, v8
	v_rndne_f32_e32 v9, v9
	v_mul_f32_e32 v10, v135, v10
	v_mul_f32_e32 v11, v135, v11
	v_rndne_f32_e32 v8, v8
	v_cvt_i32_f32_e32 v9, v9
	v_rndne_f32_e32 v10, v10
	v_rndne_f32_e32 v11, v11
; #define LAS __attribute__((address_space(3)))
; __device__ __forceinline__ float bflo(unsigned w) { return __uint_as_float(w << 16); }
; __device__ __forceinline__ float bfhi(unsigned w) { return __uint_as_float(w & 0xffff0000u); }
; __device__ __forceinline__ void direct_w8_block(const Ctx& c, LAS unsigned char* lds, const float* Wsrc, const int INC_, int srccol, unsigned char* dstrow, float* swdst) {
;     ...
; #pragma unroll
;     for (int t = 0; t < 8; ++t) { unsigned char* dt = dst + t * 64; asm volatile("" : "+v"(dt));
; #pragma unroll
;         for (int j = 0; j < 4; ++j) { v4u pk;
;             if (t < 4) { pk.x = held[t & 3][j][0]; pk.y = held[t & 3][j][1]; pk.z = held[t & 3][j][2]; pk.w = held[t & 3][j][3]; }
;             else pk = *(const LAS v4u*)(hl + ((t - 4) * 4 + j) * 1024);
;             int qi[8];
; #pragma unroll
;             for (int pr = 0; pr < 4; ++pr) { qi[2 * pr] = __float2int_rn(bflo(pk[pr]) * inv[j]); qi[2 * pr + 1] = __float2int_rn(bfhi(pk[pr]) * inv[j]); }
;             v2u w; w.x = (unsigned)(qi[0] & 255) | ((unsigned)(qi[1] & 255) << 8) | ((unsigned)(qi[2] & 255) << 16) | ((unsigned)(qi[3] & 255) << 24);
;             w.y = (unsigned)(qi[4] & 255) | ((unsigned)(qi[5] & 255) << 8) | ((unsigned)(qi[6] & 255) << 16) | ((unsigned)(qi[7] & 255) << 24);
;             *(v2u*)(dt + (size_t)j * DM) = w; } }
; __device__ __forceinline__ void phase_tail_transposes(LAS unsigned char* lds, int part, int wv) {
;     ...
;         for (int cb = c.vcu - 192; cb < NT0; cb += 64) direct_win_block(c, lds, 1, cb);
	v_cvt_i32_f32_e32 v8, v8
	v_cvt_i32_f32_sdwa v10, v10 dst_sel:WORD_1 dst_unused:UNUSED_PAD src0_sel:DWORD
	v_cvt_i32_f32_e32 v11, v11
	v_lshlrev_b32_e32 v5, 8, v5
	v_and_b32_e32 v5, 0xff00, v5
	v_and_b32_e32 v6, 0xff0000, v6
	v_perm_b32 v4, v7, v4, s81
	v_or3_b32 v4, v4, v5, v6
	v_lshlrev_b32_e32 v5, 8, v9
	s_mov_b64 s[2:3], 0xc0
	v_and_b32_e32 v5, 0xff00, v5
	v_and_b32_e32 v6, 0xff0000, v10
	v_perm_b32 v7, v11, v8, s81
	v_lshl_add_u64 v[2:3], v[0:1], 0, s[2:3]
	v_or3_b32 v5, v7, v5, v6
	global_store_dwordx2 v[2:3], v[4:5], off
	v_and_b32_e32 v5, 0xffff0000, v99
	v_cvt_pk_bf16_f32 v108, v108, v112
	v_cvt_pk_bf16_f32 v112, v115, v119
	v_lshlrev_b32_e32 v4, 16, v99
	v_mul_f32_e32 v5, v134, v5
	v_lshlrev_b32_e32 v6, 16, v107
	v_and_b32_e32 v7, 0xffff0000, v107
	v_cvt_pk_bf16_f32 v100, v100, v104
	v_cvt_pk_bf16_f32 v104, v123, v127
	v_mul_f32_e32 v4, v134, v4
	v_rndne_f32_e32 v5, v5
	v_mul_f32_e32 v6, v134, v6
	v_mul_f32_e32 v7, v134, v7
	v_and_b32_e32 v9, 0xffff0000, v112
	v_rndne_f32_e32 v4, v4
	v_cvt_i32_f32_e32 v5, v5
	v_rndne_f32_e32 v6, v6
	v_rndne_f32_e32 v7, v7
	v_lshlrev_b32_e32 v8, 16, v112
	v_mul_f32_e32 v9, v134, v9
	v_lshlrev_b32_e32 v10, 16, v104
	v_and_b32_e32 v11, 0xffff0000, v104
	v_cvt_i32_f32_e32 v4, v4
	v_cvt_i32_f32_sdwa v6, v6 dst_sel:WORD_1 dst_unused:UNUSED_PAD src0_sel:DWORD
	v_cvt_i32_f32_e32 v7, v7
	v_mul_f32_e32 v8, v134, v8
	v_rndne_f32_e32 v9, v9
	v_mul_f32_e32 v10, v134, v10
	v_mul_f32_e32 v11, v134, v11
	v_rndne_f32_e32 v8, v8
	v_cvt_i32_f32_e32 v9, v9
	v_rndne_f32_e32 v10, v10
	v_rndne_f32_e32 v11, v11
	v_cvt_i32_f32_e32 v8, v8
	v_cvt_i32_f32_sdwa v10, v10 dst_sel:WORD_1 dst_unused:UNUSED_PAD src0_sel:DWORD
	v_cvt_i32_f32_e32 v11, v11
	v_lshlrev_b32_e32 v5, 8, v5
	v_and_b32_e32 v5, 0xff00, v5
	v_and_b32_e32 v6, 0xff0000, v6
	v_perm_b32 v4, v7, v4, s81
	v_or3_b32 v4, v4, v5, v6
	v_lshlrev_b32_e32 v5, 8, v9
	v_and_b32_e32 v5, 0xff00, v5
	v_and_b32_e32 v6, 0xff0000, v10
	v_perm_b32 v7, v11, v8, s81
	v_or3_b32 v5, v7, v5, v6
	v_add_co_u32_e32 v6, vcc, s67, v2
	v_cvt_pk_bf16_f32 v109, v109, v113
	s_nop 0
	v_addc_co_u32_e32 v7, vcc, 0, v3, vcc
	global_store_dwordx2 v[6:7], v[4:5], off
	v_and_b32_e32 v5, 0xffff0000, v100
	v_cvt_pk_bf16_f32 v113, v116, v120
	v_lshlrev_b32_e32 v4, 16, v100
	v_mul_f32_e32 v5, v131, v5
	v_lshlrev_b32_e32 v6, 16, v108
	v_and_b32_e32 v7, 0xffff0000, v108
	v_cvt_pk_bf16_f32 v101, v101, v105
	v_cvt_pk_bf16_f32 v105, v124, v128
	v_mul_f32_e32 v4, v131, v4
	v_rndne_f32_e32 v5, v5
	v_mul_f32_e32 v6, v131, v6
	v_mul_f32_e32 v7, v131, v7
	v_and_b32_e32 v9, 0xffff0000, v113
	v_rndne_f32_e32 v4, v4
	v_cvt_i32_f32_e32 v5, v5
	v_rndne_f32_e32 v6, v6
	v_rndne_f32_e32 v7, v7
	v_lshlrev_b32_e32 v8, 16, v113
	v_mul_f32_e32 v9, v131, v9
	v_lshlrev_b32_e32 v10, 16, v105
	v_and_b32_e32 v11, 0xffff0000, v105
	v_cvt_i32_f32_e32 v4, v4
	v_cvt_i32_f32_sdwa v6, v6 dst_sel:WORD_1 dst_unused:UNUSED_PAD src0_sel:DWORD
	v_cvt_i32_f32_e32 v7, v7
	v_mul_f32_e32 v8, v131, v8
	v_rndne_f32_e32 v9, v9
	v_mul_f32_e32 v10, v131, v10
	v_mul_f32_e32 v11, v131, v11
	v_rndne_f32_e32 v8, v8
	v_cvt_i32_f32_e32 v9, v9
	v_rndne_f32_e32 v10, v10
	v_rndne_f32_e32 v11, v11
	v_cvt_i32_f32_e32 v8, v8
	v_cvt_i32_f32_sdwa v10, v10 dst_sel:WORD_1 dst_unused:UNUSED_PAD src0_sel:DWORD
	v_cvt_i32_f32_e32 v11, v11
	v_lshlrev_b32_e32 v5, 8, v5
	v_and_b32_e32 v5, 0xff00, v5
	v_and_b32_e32 v6, 0xff0000, v6
	v_perm_b32 v4, v7, v4, s81
	v_or3_b32 v4, v4, v5, v6
	v_lshlrev_b32_e32 v5, 8, v9
	v_and_b32_e32 v5, 0xff00, v5
	v_and_b32_e32 v6, 0xff0000, v10
	v_perm_b32 v7, v11, v8, s81
	v_or3_b32 v5, v7, v5, v6
	v_add_co_u32_e32 v6, vcc, s33, v2
	v_cvt_pk_bf16_f32 v117, v117, v121
	s_nop 0
	v_addc_co_u32_e32 v7, vcc, 0, v3, vcc
	global_store_dwordx2 v[6:7], v[4:5], off
	v_and_b32_e32 v5, 0xffff0000, v101
	v_lshlrev_b32_e32 v4, 16, v101
	v_mul_f32_e32 v5, v130, v5
	v_lshlrev_b32_e32 v6, 16, v109
	v_and_b32_e32 v7, 0xffff0000, v109
	v_cvt_pk_bf16_f32 v125, v125, v129
	v_mul_f32_e32 v4, v130, v4
	v_rndne_f32_e32 v5, v5
	v_mul_f32_e32 v6, v130, v6
	v_mul_f32_e32 v7, v130, v7
	v_and_b32_e32 v9, 0xffff0000, v117
	v_rndne_f32_e32 v4, v4
	v_cvt_i32_f32_e32 v5, v5
	v_rndne_f32_e32 v6, v6
	v_rndne_f32_e32 v7, v7
	v_lshlrev_b32_e32 v8, 16, v117
	v_mul_f32_e32 v9, v130, v9
	v_lshlrev_b32_e32 v10, 16, v125
	v_and_b32_e32 v11, 0xffff0000, v125
	v_cvt_i32_f32_e32 v4, v4
	v_cvt_i32_f32_sdwa v6, v6 dst_sel:WORD_1 dst_unused:UNUSED_PAD src0_sel:DWORD
	v_cvt_i32_f32_e32 v7, v7
	v_mul_f32_e32 v8, v130, v8
	v_rndne_f32_e32 v9, v9
	v_mul_f32_e32 v10, v130, v10
	v_mul_f32_e32 v11, v130, v11
	v_rndne_f32_e32 v8, v8
	v_cvt_i32_f32_e32 v9, v9
	v_rndne_f32_e32 v10, v10
	v_rndne_f32_e32 v11, v11
	v_cvt_i32_f32_e32 v8, v8
	v_cvt_i32_f32_sdwa v10, v10 dst_sel:WORD_1 dst_unused:UNUSED_PAD src0_sel:DWORD
	v_cvt_i32_f32_e32 v11, v11
	v_lshlrev_b32_e32 v5, 8, v5
	v_and_b32_e32 v5, 0xff00, v5
	v_and_b32_e32 v6, 0xff0000, v6
	v_perm_b32 v4, v7, v4, s81
	v_or3_b32 v4, v4, v5, v6
	v_lshlrev_b32_e32 v5, 8, v9
	v_and_b32_e32 v5, 0xff00, v5
	v_and_b32_e32 v6, 0xff0000, v10
	v_perm_b32 v7, v11, v8, s81
	v_add_co_u32_e32 v2, vcc, s44, v2
	s_mov_b64 s[2:3], 0x100
	v_or3_b32 v5, v7, v5, v6
	v_addc_co_u32_e32 v3, vcc, 0, v3, vcc
	v_lshl_add_u64 v[6:7], v[0:1], 0, s[2:3]
	global_store_dwordx2 v[2:3], v[4:5], off
	ds_read_b128 v[2:5], v96
	s_mov_b64 s[2:3], 0x140
	s_add_i32 s1, s1, 64
	s_addk_i32 s10, 0x20
	s_cmp_gt_i32 s1, 63
	s_waitcnt lgkmcnt(0)
; #define LAS __attribute__((address_space(3)))
; __device__ __forceinline__ float bflo(unsigned w) { return __uint_as_float(w << 16); }
; __device__ __forceinline__ float bfhi(unsigned w) { return __uint_as_float(w & 0xffff0000u); }
; __device__ __forceinline__ void direct_w8_block(const Ctx& c, LAS unsigned char* lds, const float* Wsrc, const int INC_, int srccol, unsigned char* dstrow, float* swdst) {
;     ...
; #pragma unroll
;     for (int t = 0; t < 8; ++t) { unsigned char* dt = dst + t * 64; asm volatile("" : "+v"(dt));
; #pragma unroll
;         for (int j = 0; j < 4; ++j) { v4u pk;
;             if (t < 4) { pk.x = held[t & 3][j][0]; pk.y = held[t & 3][j][1]; pk.z = held[t & 3][j][2]; pk.w = held[t & 3][j][3]; }
;             else pk = *(const LAS v4u*)(hl + ((t - 4) * 4 + j) * 1024);
;             int qi[8];
; #pragma unroll
;             for (int pr = 0; pr < 4; ++pr) { qi[2 * pr] = __float2int_rn(bflo(pk[pr]) * inv[j]); qi[2 * pr + 1] = __float2int_rn(bfhi(pk[pr]) * inv[j]); }
;             v2u w; w.x = (unsigned)(qi[0] & 255) | ((unsigned)(qi[1] & 255) << 8) | ((unsigned)(qi[2] & 255) << 16) | ((unsigned)(qi[3] & 255) << 24);
;             w.y = (unsigned)(qi[4] & 255) | ((unsigned)(qi[5] & 255) << 8) | ((unsigned)(qi[6] & 255) << 16) | ((unsigned)(qi[7] & 255) << 24);
;             *(v2u*)(dt + (size_t)j * DM) = w; } }
	v_lshlrev_b32_e32 v8, 16, v2
	v_and_b32_e32 v2, 0xffff0000, v2
	v_mul_f32_e32 v2, v135, v2
	v_lshlrev_b32_e32 v9, 16, v3
	v_and_b32_e32 v3, 0xffff0000, v3
	v_mul_f32_e32 v8, v135, v8
	v_rndne_f32_e32 v2, v2
	v_mul_f32_e32 v9, v135, v9
	v_mul_f32_e32 v3, v135, v3
	v_lshlrev_b32_e32 v10, 16, v4
	v_and_b32_e32 v4, 0xffff0000, v4
	v_rndne_f32_e32 v8, v8
	v_cvt_i32_f32_e32 v2, v2
	v_rndne_f32_e32 v9, v9
	v_rndne_f32_e32 v3, v3
	v_mul_f32_e32 v4, v135, v4
	v_lshlrev_b32_e32 v11, 16, v5
	v_and_b32_e32 v5, 0xffff0000, v5
	v_cvt_i32_f32_e32 v8, v8
	v_cvt_i32_f32_sdwa v9, v9 dst_sel:WORD_1 dst_unused:UNUSED_PAD src0_sel:DWORD
	v_cvt_i32_f32_e32 v3, v3
	v_mul_f32_e32 v10, v135, v10
	v_rndne_f32_e32 v4, v4
	v_mul_f32_e32 v11, v135, v11
	v_mul_f32_e32 v5, v135, v5
	v_rndne_f32_e32 v10, v10
	v_cvt_i32_f32_e32 v4, v4
	v_rndne_f32_e32 v11, v11
	v_rndne_f32_e32 v5, v5
	v_cvt_i32_f32_e32 v10, v10
	v_cvt_i32_f32_sdwa v11, v11 dst_sel:WORD_1 dst_unused:UNUSED_PAD src0_sel:DWORD
	v_cvt_i32_f32_e32 v5, v5
	v_lshlrev_b32_e32 v2, 8, v2
	v_and_b32_e32 v2, 0xff00, v2
	v_and_b32_e32 v9, 0xff0000, v9
	v_perm_b32 v3, v3, v8, s81
	v_or3_b32 v2, v3, v2, v9
	v_lshlrev_b32_e32 v3, 8, v4
	v_and_b32_e32 v3, 0xff00, v3
	v_and_b32_e32 v4, 0xff0000, v11
	v_perm_b32 v5, v5, v10, s81
	v_or3_b32 v3, v5, v3, v4
	global_store_dwordx2 v[6:7], v[2:3], off
	ds_read_b128 v[2:5], v96 offset:1024
	s_waitcnt lgkmcnt(0)
	v_lshlrev_b32_e32 v8, 16, v2
	v_and_b32_e32 v2, 0xffff0000, v2
	v_mul_f32_e32 v2, v134, v2
	v_lshlrev_b32_e32 v9, 16, v3
	v_and_b32_e32 v3, 0xffff0000, v3
	v_mul_f32_e32 v8, v134, v8
	v_rndne_f32_e32 v2, v2
	v_mul_f32_e32 v9, v134, v9
	v_mul_f32_e32 v3, v134, v3
	v_lshlrev_b32_e32 v10, 16, v4
	v_and_b32_e32 v4, 0xffff0000, v4
	v_rndne_f32_e32 v8, v8
	v_cvt_i32_f32_e32 v2, v2
	v_rndne_f32_e32 v9, v9
	v_rndne_f32_e32 v3, v3
	v_mul_f32_e32 v4, v134, v4
	v_lshlrev_b32_e32 v11, 16, v5
	v_and_b32_e32 v5, 0xffff0000, v5
	v_cvt_i32_f32_e32 v8, v8
	v_cvt_i32_f32_sdwa v9, v9 dst_sel:WORD_1 dst_unused:UNUSED_PAD src0_sel:DWORD
	v_cvt_i32_f32_e32 v3, v3
	v_mul_f32_e32 v10, v134, v10
	v_rndne_f32_e32 v4, v4
	v_mul_f32_e32 v11, v134, v11
	v_mul_f32_e32 v5, v134, v5
	v_rndne_f32_e32 v10, v10
	v_cvt_i32_f32_e32 v4, v4
	v_rndne_f32_e32 v11, v11
	v_rndne_f32_e32 v5, v5
	v_cvt_i32_f32_e32 v10, v10
	v_cvt_i32_f32_sdwa v11, v11 dst_sel:WORD_1 dst_unused:UNUSED_PAD src0_sel:DWORD
	v_cvt_i32_f32_e32 v5, v5
	v_lshlrev_b32_e32 v2, 8, v2
	v_and_b32_e32 v2, 0xff00, v2
	v_and_b32_e32 v9, 0xff0000, v9
	v_perm_b32 v3, v3, v8, s81
	v_or3_b32 v2, v3, v2, v9
	v_lshlrev_b32_e32 v3, 8, v4
	v_and_b32_e32 v3, 0xff00, v3
	v_and_b32_e32 v4, 0xff0000, v11
	v_perm_b32 v5, v5, v10, s81
	v_or3_b32 v3, v5, v3, v4
	v_add_co_u32_e32 v4, vcc, s67, v6
	s_nop 1
	v_addc_co_u32_e32 v5, vcc, 0, v7, vcc
	global_store_dwordx2 v[4:5], v[2:3], off
	ds_read_b128 v[2:5], v96 offset:2048
	s_waitcnt lgkmcnt(0)
	v_lshlrev_b32_e32 v8, 16, v2
	v_and_b32_e32 v2, 0xffff0000, v2
	v_mul_f32_e32 v2, v131, v2
	v_lshlrev_b32_e32 v9, 16, v3
	v_and_b32_e32 v3, 0xffff0000, v3
	v_mul_f32_e32 v8, v131, v8
	v_rndne_f32_e32 v2, v2
	v_mul_f32_e32 v9, v131, v9
	v_mul_f32_e32 v3, v131, v3
	v_lshlrev_b32_e32 v10, 16, v4
	v_and_b32_e32 v4, 0xffff0000, v4
	v_rndne_f32_e32 v8, v8
	v_cvt_i32_f32_e32 v2, v2
	v_rndne_f32_e32 v9, v9
	v_rndne_f32_e32 v3, v3
	v_mul_f32_e32 v4, v131, v4
	v_lshlrev_b32_e32 v11, 16, v5
	v_and_b32_e32 v5, 0xffff0000, v5
	v_cvt_i32_f32_e32 v8, v8
	v_cvt_i32_f32_sdwa v9, v9 dst_sel:WORD_1 dst_unused:UNUSED_PAD src0_sel:DWORD
	v_cvt_i32_f32_e32 v3, v3
	v_mul_f32_e32 v10, v131, v10
	v_rndne_f32_e32 v4, v4
	v_mul_f32_e32 v11, v131, v11
	v_mul_f32_e32 v5, v131, v5
	v_rndne_f32_e32 v10, v10
	v_cvt_i32_f32_e32 v4, v4
	v_rndne_f32_e32 v11, v11
	v_rndne_f32_e32 v5, v5
	v_cvt_i32_f32_e32 v10, v10
	v_cvt_i32_f32_sdwa v11, v11 dst_sel:WORD_1 dst_unused:UNUSED_PAD src0_sel:DWORD
	v_cvt_i32_f32_e32 v5, v5
	v_lshlrev_b32_e32 v2, 8, v2
	v_and_b32_e32 v2, 0xff00, v2
	v_and_b32_e32 v9, 0xff0000, v9
	v_perm_b32 v3, v3, v8, s81
	v_or3_b32 v2, v3, v2, v9
	v_lshlrev_b32_e32 v3, 8, v4
	v_and_b32_e32 v3, 0xff00, v3
	v_and_b32_e32 v4, 0xff0000, v11
	v_perm_b32 v5, v5, v10, s81
	v_or3_b32 v3, v5, v3, v4
	v_add_co_u32_e32 v4, vcc, s33, v6
	s_nop 1
	v_addc_co_u32_e32 v5, vcc, 0, v7, vcc
	global_store_dwordx2 v[4:5], v[2:3], off
	ds_read_b128 v[2:5], v96 offset:3072
	s_waitcnt lgkmcnt(0)
	v_lshlrev_b32_e32 v8, 16, v2
	v_and_b32_e32 v2, 0xffff0000, v2
	v_mul_f32_e32 v2, v130, v2
	v_lshlrev_b32_e32 v9, 16, v3
	v_and_b32_e32 v3, 0xffff0000, v3
	v_mul_f32_e32 v8, v130, v8
	v_rndne_f32_e32 v2, v2
	v_mul_f32_e32 v9, v130, v9
	v_mul_f32_e32 v3, v130, v3
	v_lshlrev_b32_e32 v10, 16, v4
	v_and_b32_e32 v4, 0xffff0000, v4
	v_rndne_f32_e32 v8, v8
	v_cvt_i32_f32_e32 v2, v2
	v_rndne_f32_e32 v9, v9
	v_rndne_f32_e32 v3, v3
	v_mul_f32_e32 v4, v130, v4
	v_lshlrev_b32_e32 v11, 16, v5
	v_and_b32_e32 v5, 0xffff0000, v5
	v_cvt_i32_f32_e32 v8, v8
	v_cvt_i32_f32_sdwa v9, v9 dst_sel:WORD_1 dst_unused:UNUSED_PAD src0_sel:DWORD
	v_cvt_i32_f32_e32 v3, v3
	v_mul_f32_e32 v10, v130, v10
	v_rndne_f32_e32 v4, v4
	v_mul_f32_e32 v11, v130, v11
	v_mul_f32_e32 v5, v130, v5
	v_rndne_f32_e32 v10, v10
	v_cvt_i32_f32_e32 v4, v4
	v_rndne_f32_e32 v11, v11
	v_rndne_f32_e32 v5, v5
	v_cvt_i32_f32_e32 v10, v10
	v_cvt_i32_f32_sdwa v11, v11 dst_sel:WORD_1 dst_unused:UNUSED_PAD src0_sel:DWORD
	v_cvt_i32_f32_e32 v5, v5
	v_lshlrev_b32_e32 v2, 8, v2
	v_and_b32_e32 v2, 0xff00, v2
	v_and_b32_e32 v9, 0xff0000, v9
	v_perm_b32 v3, v3, v8, s81
	v_or3_b32 v2, v3, v2, v9
	v_lshlrev_b32_e32 v3, 8, v4
	v_and_b32_e32 v3, 0xff00, v3
	v_and_b32_e32 v4, 0xff0000, v11
	v_perm_b32 v5, v5, v10, s81
	v_or3_b32 v3, v5, v3, v4
	v_add_co_u32_e32 v4, vcc, s44, v6
	s_nop 1
	v_addc_co_u32_e32 v5, vcc, 0, v7, vcc
	v_lshl_add_u64 v[6:7], v[0:1], 0, s[2:3]
	global_store_dwordx2 v[4:5], v[2:3], off
	ds_read_b128 v[2:5], v96 offset:4096
	s_mov_b64 s[2:3], 0x180
	s_waitcnt lgkmcnt(0)
; #define LAS __attribute__((address_space(3)))
; __device__ __forceinline__ float bflo(unsigned w) { return __uint_as_float(w << 16); }
; __device__ __forceinline__ float bfhi(unsigned w) { return __uint_as_float(w & 0xffff0000u); }
; __device__ __forceinline__ void direct_w8_block(const Ctx& c, LAS unsigned char* lds, const float* Wsrc, const int INC_, int srccol, unsigned char* dstrow, float* swdst) {
;     ...
; #pragma unroll
;     for (int t = 0; t < 8; ++t) { unsigned char* dt = dst + t * 64; asm volatile("" : "+v"(dt));
; #pragma unroll
;         for (int j = 0; j < 4; ++j) { v4u pk;
;             if (t < 4) { pk.x = held[t & 3][j][0]; pk.y = held[t & 3][j][1]; pk.z = held[t & 3][j][2]; pk.w = held[t & 3][j][3]; }
;             else pk = *(const LAS v4u*)(hl + ((t - 4) * 4 + j) * 1024);
;             int qi[8];
; #pragma unroll
;             for (int pr = 0; pr < 4; ++pr) { qi[2 * pr] = __float2int_rn(bflo(pk[pr]) * inv[j]); qi[2 * pr + 1] = __float2int_rn(bfhi(pk[pr]) * inv[j]); }
;             v2u w; w.x = (unsigned)(qi[0] & 255) | ((unsigned)(qi[1] & 255) << 8) | ((unsigned)(qi[2] & 255) << 16) | ((unsigned)(qi[3] & 255) << 24);
;             w.y = (unsigned)(qi[4] & 255) | ((unsigned)(qi[5] & 255) << 8) | ((unsigned)(qi[6] & 255) << 16) | ((unsigned)(qi[7] & 255) << 24);
;             *(v2u*)(dt + (size_t)j * DM) = w; } }
	v_lshlrev_b32_e32 v8, 16, v2
	v_and_b32_e32 v2, 0xffff0000, v2
	v_mul_f32_e32 v2, v135, v2
	v_lshlrev_b32_e32 v9, 16, v3
	v_and_b32_e32 v3, 0xffff0000, v3
	v_mul_f32_e32 v8, v135, v8
	v_rndne_f32_e32 v2, v2
	v_mul_f32_e32 v9, v135, v9
	v_mul_f32_e32 v3, v135, v3
	v_lshlrev_b32_e32 v10, 16, v4
	v_and_b32_e32 v4, 0xffff0000, v4
	v_rndne_f32_e32 v8, v8
	v_cvt_i32_f32_e32 v2, v2
	v_rndne_f32_e32 v9, v9
	v_rndne_f32_e32 v3, v3
	v_mul_f32_e32 v4, v135, v4
	v_lshlrev_b32_e32 v11, 16, v5
	v_and_b32_e32 v5, 0xffff0000, v5
	v_cvt_i32_f32_e32 v8, v8
	v_cvt_i32_f32_sdwa v9, v9 dst_sel:WORD_1 dst_unused:UNUSED_PAD src0_sel:DWORD
	v_cvt_i32_f32_e32 v3, v3
	v_mul_f32_e32 v10, v135, v10
	v_rndne_f32_e32 v4, v4
	v_mul_f32_e32 v11, v135, v11
	v_mul_f32_e32 v5, v135, v5
	v_rndne_f32_e32 v10, v10
	v_cvt_i32_f32_e32 v4, v4
	v_rndne_f32_e32 v11, v11
	v_rndne_f32_e32 v5, v5
	v_cvt_i32_f32_e32 v10, v10
	v_cvt_i32_f32_sdwa v11, v11 dst_sel:WORD_1 dst_unused:UNUSED_PAD src0_sel:DWORD
	v_cvt_i32_f32_e32 v5, v5
	v_lshlrev_b32_e32 v2, 8, v2
	v_and_b32_e32 v2, 0xff00, v2
	v_and_b32_e32 v9, 0xff0000, v9
	v_perm_b32 v3, v3, v8, s81
	v_or3_b32 v2, v3, v2, v9
	v_lshlrev_b32_e32 v3, 8, v4
	v_and_b32_e32 v3, 0xff00, v3
	v_and_b32_e32 v4, 0xff0000, v11
	v_perm_b32 v5, v5, v10, s81
	v_or3_b32 v3, v5, v3, v4
	global_store_dwordx2 v[6:7], v[2:3], off
	ds_read_b128 v[2:5], v96 offset:5120
	s_waitcnt lgkmcnt(0)
	v_lshlrev_b32_e32 v8, 16, v2
	v_and_b32_e32 v2, 0xffff0000, v2
	v_mul_f32_e32 v2, v134, v2
	v_lshlrev_b32_e32 v9, 16, v3
	v_and_b32_e32 v3, 0xffff0000, v3
	v_mul_f32_e32 v8, v134, v8
	v_rndne_f32_e32 v2, v2
	v_mul_f32_e32 v9, v134, v9
	v_mul_f32_e32 v3, v134, v3
	v_lshlrev_b32_e32 v10, 16, v4
	v_and_b32_e32 v4, 0xffff0000, v4
	v_rndne_f32_e32 v8, v8
	v_cvt_i32_f32_e32 v2, v2
	v_rndne_f32_e32 v9, v9
	v_rndne_f32_e32 v3, v3
	v_mul_f32_e32 v4, v134, v4
	v_lshlrev_b32_e32 v11, 16, v5
	v_and_b32_e32 v5, 0xffff0000, v5
	v_cvt_i32_f32_e32 v8, v8
	v_cvt_i32_f32_sdwa v9, v9 dst_sel:WORD_1 dst_unused:UNUSED_PAD src0_sel:DWORD
	v_cvt_i32_f32_e32 v3, v3
	v_mul_f32_e32 v10, v134, v10
	v_rndne_f32_e32 v4, v4
	v_mul_f32_e32 v11, v134, v11
	v_mul_f32_e32 v5, v134, v5
	v_rndne_f32_e32 v10, v10
	v_cvt_i32_f32_e32 v4, v4
	v_rndne_f32_e32 v11, v11
	v_rndne_f32_e32 v5, v5
	v_cvt_i32_f32_e32 v10, v10
	v_cvt_i32_f32_sdwa v11, v11 dst_sel:WORD_1 dst_unused:UNUSED_PAD src0_sel:DWORD
	v_cvt_i32_f32_e32 v5, v5
	v_lshlrev_b32_e32 v2, 8, v2
	v_and_b32_e32 v2, 0xff00, v2
	v_and_b32_e32 v9, 0xff0000, v9
	v_perm_b32 v3, v3, v8, s81
	v_or3_b32 v2, v3, v2, v9
	v_lshlrev_b32_e32 v3, 8, v4
	v_and_b32_e32 v3, 0xff00, v3
	v_and_b32_e32 v4, 0xff0000, v11
	v_perm_b32 v5, v5, v10, s81
	v_or3_b32 v3, v5, v3, v4
	v_add_co_u32_e32 v4, vcc, s67, v6
	s_nop 1
	v_addc_co_u32_e32 v5, vcc, 0, v7, vcc
	global_store_dwordx2 v[4:5], v[2:3], off
	ds_read_b128 v[2:5], v96 offset:6144
	s_waitcnt lgkmcnt(0)
	v_lshlrev_b32_e32 v8, 16, v2
	v_and_b32_e32 v2, 0xffff0000, v2
	v_mul_f32_e32 v2, v131, v2
	v_lshlrev_b32_e32 v9, 16, v3
	v_and_b32_e32 v3, 0xffff0000, v3
	v_mul_f32_e32 v8, v131, v8
	v_rndne_f32_e32 v2, v2
	v_mul_f32_e32 v9, v131, v9
	v_mul_f32_e32 v3, v131, v3
	v_lshlrev_b32_e32 v10, 16, v4
	v_and_b32_e32 v4, 0xffff0000, v4
	v_rndne_f32_e32 v8, v8
	v_cvt_i32_f32_e32 v2, v2
	v_rndne_f32_e32 v9, v9
	v_rndne_f32_e32 v3, v3
	v_mul_f32_e32 v4, v131, v4
	v_lshlrev_b32_e32 v11, 16, v5
	v_and_b32_e32 v5, 0xffff0000, v5
	v_cvt_i32_f32_e32 v8, v8
	v_cvt_i32_f32_sdwa v9, v9 dst_sel:WORD_1 dst_unused:UNUSED_PAD src0_sel:DWORD
	v_cvt_i32_f32_e32 v3, v3
	v_mul_f32_e32 v10, v131, v10
	v_rndne_f32_e32 v4, v4
	v_mul_f32_e32 v11, v131, v11
	v_mul_f32_e32 v5, v131, v5
	v_rndne_f32_e32 v10, v10
	v_cvt_i32_f32_e32 v4, v4
	v_rndne_f32_e32 v11, v11
	v_rndne_f32_e32 v5, v5
	v_cvt_i32_f32_e32 v10, v10
	v_cvt_i32_f32_sdwa v11, v11 dst_sel:WORD_1 dst_unused:UNUSED_PAD src0_sel:DWORD
	v_cvt_i32_f32_e32 v5, v5
	v_lshlrev_b32_e32 v2, 8, v2
	v_and_b32_e32 v2, 0xff00, v2
	v_and_b32_e32 v9, 0xff0000, v9
	v_perm_b32 v3, v3, v8, s81
	v_or3_b32 v2, v3, v2, v9
	v_lshlrev_b32_e32 v3, 8, v4
	v_and_b32_e32 v3, 0xff00, v3
	v_and_b32_e32 v4, 0xff0000, v11
	v_perm_b32 v5, v5, v10, s81
	v_or3_b32 v3, v5, v3, v4
	v_add_co_u32_e32 v4, vcc, s33, v6
	s_nop 1
	v_addc_co_u32_e32 v5, vcc, 0, v7, vcc
	global_store_dwordx2 v[4:5], v[2:3], off
	ds_read_b128 v[2:5], v96 offset:7168
	s_waitcnt lgkmcnt(0)
	v_lshlrev_b32_e32 v8, 16, v2
	v_and_b32_e32 v2, 0xffff0000, v2
	v_mul_f32_e32 v2, v130, v2
	v_lshlrev_b32_e32 v9, 16, v3
	v_and_b32_e32 v3, 0xffff0000, v3
	v_mul_f32_e32 v8, v130, v8
	v_rndne_f32_e32 v2, v2
	v_mul_f32_e32 v9, v130, v9
	v_mul_f32_e32 v3, v130, v3
	v_lshlrev_b32_e32 v10, 16, v4
	v_and_b32_e32 v4, 0xffff0000, v4
	v_rndne_f32_e32 v8, v8
	v_cvt_i32_f32_e32 v2, v2
	v_rndne_f32_e32 v9, v9
	v_rndne_f32_e32 v3, v3
	v_mul_f32_e32 v4, v130, v4
	v_lshlrev_b32_e32 v11, 16, v5
	v_and_b32_e32 v5, 0xffff0000, v5
	v_cvt_i32_f32_e32 v8, v8
	v_cvt_i32_f32_sdwa v9, v9 dst_sel:WORD_1 dst_unused:UNUSED_PAD src0_sel:DWORD
	v_cvt_i32_f32_e32 v3, v3
	v_mul_f32_e32 v10, v130, v10
	v_rndne_f32_e32 v4, v4
	v_mul_f32_e32 v11, v130, v11
	v_mul_f32_e32 v5, v130, v5
	v_rndne_f32_e32 v10, v10
	v_cvt_i32_f32_e32 v4, v4
	v_rndne_f32_e32 v11, v11
	v_rndne_f32_e32 v5, v5
	v_cvt_i32_f32_e32 v10, v10
	v_cvt_i32_f32_sdwa v11, v11 dst_sel:WORD_1 dst_unused:UNUSED_PAD src0_sel:DWORD
	v_cvt_i32_f32_e32 v5, v5
	v_lshlrev_b32_e32 v2, 8, v2
	v_and_b32_e32 v2, 0xff00, v2
	v_and_b32_e32 v9, 0xff0000, v9
	v_perm_b32 v3, v3, v8, s81
	v_or3_b32 v2, v3, v2, v9
	v_lshlrev_b32_e32 v3, 8, v4
	v_and_b32_e32 v3, 0xff00, v3
	v_and_b32_e32 v4, 0xff0000, v11
	v_perm_b32 v5, v5, v10, s81
	v_or3_b32 v3, v5, v3, v4
	v_add_co_u32_e32 v4, vcc, s44, v6
	s_nop 1
	v_addc_co_u32_e32 v5, vcc, 0, v7, vcc
	v_lshl_add_u64 v[6:7], v[0:1], 0, s[2:3]
	global_store_dwordx2 v[4:5], v[2:3], off
	ds_read_b128 v[2:5], v96 offset:8192
	s_mov_b64 s[2:3], 0x1c0
	s_waitcnt lgkmcnt(0)
; #define LAS __attribute__((address_space(3)))
; __device__ __forceinline__ float bflo(unsigned w) { return __uint_as_float(w << 16); }
; __device__ __forceinline__ float bfhi(unsigned w) { return __uint_as_float(w & 0xffff0000u); }
; __device__ __forceinline__ void direct_w8_block(const Ctx& c, LAS unsigned char* lds, const float* Wsrc, const int INC_, int srccol, unsigned char* dstrow, float* swdst) {
;     ...
; #pragma unroll
;     for (int t = 0; t < 8; ++t) { unsigned char* dt = dst + t * 64; asm volatile("" : "+v"(dt));
; #pragma unroll
;         for (int j = 0; j < 4; ++j) { v4u pk;
;             if (t < 4) { pk.x = held[t & 3][j][0]; pk.y = held[t & 3][j][1]; pk.z = held[t & 3][j][2]; pk.w = held[t & 3][j][3]; }
;             else pk = *(const LAS v4u*)(hl + ((t - 4) * 4 + j) * 1024);
;             int qi[8];
; #pragma unroll
;             for (int pr = 0; pr < 4; ++pr) { qi[2 * pr] = __float2int_rn(bflo(pk[pr]) * inv[j]); qi[2 * pr + 1] = __float2int_rn(bfhi(pk[pr]) * inv[j]); }
;             v2u w; w.x = (unsigned)(qi[0] & 255) | ((unsigned)(qi[1] & 255) << 8) | ((unsigned)(qi[2] & 255) << 16) | ((unsigned)(qi[3] & 255) << 24);
;             w.y = (unsigned)(qi[4] & 255) | ((unsigned)(qi[5] & 255) << 8) | ((unsigned)(qi[6] & 255) << 16) | ((unsigned)(qi[7] & 255) << 24);
;             *(v2u*)(dt + (size_t)j * DM) = w; } }
	v_lshlrev_b32_e32 v8, 16, v2
	v_and_b32_e32 v2, 0xffff0000, v2
	v_mul_f32_e32 v2, v135, v2
	v_lshlrev_b32_e32 v9, 16, v3
	v_and_b32_e32 v3, 0xffff0000, v3
	v_mul_f32_e32 v8, v135, v8
	v_rndne_f32_e32 v2, v2
	v_mul_f32_e32 v9, v135, v9
	v_mul_f32_e32 v3, v135, v3
	v_lshlrev_b32_e32 v10, 16, v4
	v_and_b32_e32 v4, 0xffff0000, v4
	v_rndne_f32_e32 v8, v8
	v_cvt_i32_f32_e32 v2, v2
	v_rndne_f32_e32 v9, v9
	v_rndne_f32_e32 v3, v3
	v_mul_f32_e32 v4, v135, v4
	v_lshlrev_b32_e32 v11, 16, v5
	v_and_b32_e32 v5, 0xffff0000, v5
	v_cvt_i32_f32_e32 v8, v8
	v_cvt_i32_f32_sdwa v9, v9 dst_sel:WORD_1 dst_unused:UNUSED_PAD src0_sel:DWORD
	v_cvt_i32_f32_e32 v3, v3
	v_mul_f32_e32 v10, v135, v10
	v_rndne_f32_e32 v4, v4
	v_mul_f32_e32 v11, v135, v11
	v_mul_f32_e32 v5, v135, v5
	v_rndne_f32_e32 v10, v10
	v_cvt_i32_f32_e32 v4, v4
	v_rndne_f32_e32 v11, v11
	v_rndne_f32_e32 v5, v5
	v_cvt_i32_f32_e32 v10, v10
	v_cvt_i32_f32_sdwa v11, v11 dst_sel:WORD_1 dst_unused:UNUSED_PAD src0_sel:DWORD
	v_cvt_i32_f32_e32 v5, v5
	v_lshlrev_b32_e32 v2, 8, v2
	v_and_b32_e32 v2, 0xff00, v2
	v_and_b32_e32 v9, 0xff0000, v9
	v_perm_b32 v3, v3, v8, s81
	v_or3_b32 v2, v3, v2, v9
	v_lshlrev_b32_e32 v3, 8, v4
	v_and_b32_e32 v3, 0xff00, v3
	v_and_b32_e32 v4, 0xff0000, v11
	v_perm_b32 v5, v5, v10, s81
	v_or3_b32 v3, v5, v3, v4
	global_store_dwordx2 v[6:7], v[2:3], off
	ds_read_b128 v[2:5], v96 offset:9216
	s_waitcnt lgkmcnt(0)
	v_lshlrev_b32_e32 v8, 16, v2
	v_and_b32_e32 v2, 0xffff0000, v2
	v_mul_f32_e32 v2, v134, v2
	v_lshlrev_b32_e32 v9, 16, v3
	v_and_b32_e32 v3, 0xffff0000, v3
	v_mul_f32_e32 v8, v134, v8
	v_rndne_f32_e32 v2, v2
	v_mul_f32_e32 v9, v134, v9
	v_mul_f32_e32 v3, v134, v3
	v_lshlrev_b32_e32 v10, 16, v4
	v_and_b32_e32 v4, 0xffff0000, v4
	v_rndne_f32_e32 v8, v8
	v_cvt_i32_f32_e32 v2, v2
	v_rndne_f32_e32 v9, v9
	v_rndne_f32_e32 v3, v3
	v_mul_f32_e32 v4, v134, v4
	v_lshlrev_b32_e32 v11, 16, v5
	v_and_b32_e32 v5, 0xffff0000, v5
	v_cvt_i32_f32_e32 v8, v8
	v_cvt_i32_f32_sdwa v9, v9 dst_sel:WORD_1 dst_unused:UNUSED_PAD src0_sel:DWORD
	v_cvt_i32_f32_e32 v3, v3
	v_mul_f32_e32 v10, v134, v10
	v_rndne_f32_e32 v4, v4
	v_mul_f32_e32 v11, v134, v11
	v_mul_f32_e32 v5, v134, v5
	v_rndne_f32_e32 v10, v10
	v_cvt_i32_f32_e32 v4, v4
	v_rndne_f32_e32 v11, v11
	v_rndne_f32_e32 v5, v5
	v_cvt_i32_f32_e32 v10, v10
	v_cvt_i32_f32_sdwa v11, v11 dst_sel:WORD_1 dst_unused:UNUSED_PAD src0_sel:DWORD
	v_cvt_i32_f32_e32 v5, v5
	v_lshlrev_b32_e32 v2, 8, v2
	v_and_b32_e32 v2, 0xff00, v2
	v_and_b32_e32 v9, 0xff0000, v9
	v_perm_b32 v3, v3, v8, s81
	v_or3_b32 v2, v3, v2, v9
	v_lshlrev_b32_e32 v3, 8, v4
	v_and_b32_e32 v3, 0xff00, v3
	v_and_b32_e32 v4, 0xff0000, v11
	v_perm_b32 v5, v5, v10, s81
	v_or3_b32 v3, v5, v3, v4
	v_add_co_u32_e32 v4, vcc, s67, v6
	s_nop 1
	v_addc_co_u32_e32 v5, vcc, 0, v7, vcc
	global_store_dwordx2 v[4:5], v[2:3], off
	ds_read_b128 v[2:5], v96 offset:10240
	s_waitcnt lgkmcnt(0)
	v_lshlrev_b32_e32 v8, 16, v2
	v_and_b32_e32 v2, 0xffff0000, v2
	v_mul_f32_e32 v2, v131, v2
	v_lshlrev_b32_e32 v9, 16, v3
	v_and_b32_e32 v3, 0xffff0000, v3
	v_mul_f32_e32 v8, v131, v8
	v_rndne_f32_e32 v2, v2
	v_mul_f32_e32 v9, v131, v9
	v_mul_f32_e32 v3, v131, v3
	v_lshlrev_b32_e32 v10, 16, v4
	v_and_b32_e32 v4, 0xffff0000, v4
	v_rndne_f32_e32 v8, v8
	v_cvt_i32_f32_e32 v2, v2
	v_rndne_f32_e32 v9, v9
	v_rndne_f32_e32 v3, v3
	v_mul_f32_e32 v4, v131, v4
	v_lshlrev_b32_e32 v11, 16, v5
	v_and_b32_e32 v5, 0xffff0000, v5
	v_cvt_i32_f32_e32 v8, v8
	v_cvt_i32_f32_sdwa v9, v9 dst_sel:WORD_1 dst_unused:UNUSED_PAD src0_sel:DWORD
	v_cvt_i32_f32_e32 v3, v3
	v_mul_f32_e32 v10, v131, v10
	v_rndne_f32_e32 v4, v4
	v_mul_f32_e32 v11, v131, v11
	v_mul_f32_e32 v5, v131, v5
	v_rndne_f32_e32 v10, v10
	v_cvt_i32_f32_e32 v4, v4
	v_rndne_f32_e32 v11, v11
	v_rndne_f32_e32 v5, v5
	v_cvt_i32_f32_e32 v10, v10
	v_cvt_i32_f32_sdwa v11, v11 dst_sel:WORD_1 dst_unused:UNUSED_PAD src0_sel:DWORD
	v_cvt_i32_f32_e32 v5, v5
	v_lshlrev_b32_e32 v2, 8, v2
	v_and_b32_e32 v2, 0xff00, v2
	v_and_b32_e32 v9, 0xff0000, v9
	v_perm_b32 v3, v3, v8, s81
	v_or3_b32 v2, v3, v2, v9
	v_lshlrev_b32_e32 v3, 8, v4
	v_and_b32_e32 v3, 0xff00, v3
	v_and_b32_e32 v4, 0xff0000, v11
	v_perm_b32 v5, v5, v10, s81
	v_or3_b32 v3, v5, v3, v4
	v_add_co_u32_e32 v4, vcc, s33, v6
	s_nop 1
	v_addc_co_u32_e32 v5, vcc, 0, v7, vcc
	global_store_dwordx2 v[4:5], v[2:3], off
	ds_read_b128 v[2:5], v96 offset:11264
	s_waitcnt lgkmcnt(0)
	v_lshlrev_b32_e32 v8, 16, v2
	v_and_b32_e32 v2, 0xffff0000, v2
	v_mul_f32_e32 v2, v130, v2
	v_lshlrev_b32_e32 v9, 16, v3
	v_and_b32_e32 v3, 0xffff0000, v3
	v_mul_f32_e32 v8, v130, v8
	v_rndne_f32_e32 v2, v2
	v_mul_f32_e32 v9, v130, v9
	v_mul_f32_e32 v3, v130, v3
	v_lshlrev_b32_e32 v10, 16, v4
	v_and_b32_e32 v4, 0xffff0000, v4
	v_rndne_f32_e32 v8, v8
	v_cvt_i32_f32_e32 v2, v2
	v_rndne_f32_e32 v9, v9
	v_rndne_f32_e32 v3, v3
	v_mul_f32_e32 v4, v130, v4
	v_lshlrev_b32_e32 v11, 16, v5
	v_and_b32_e32 v5, 0xffff0000, v5
	v_cvt_i32_f32_e32 v8, v8
	v_cvt_i32_f32_sdwa v9, v9 dst_sel:WORD_1 dst_unused:UNUSED_PAD src0_sel:DWORD
	v_cvt_i32_f32_e32 v3, v3
	v_mul_f32_e32 v10, v130, v10
	v_rndne_f32_e32 v4, v4
	v_mul_f32_e32 v11, v130, v11
	v_mul_f32_e32 v5, v130, v5
	v_rndne_f32_e32 v10, v10
	v_cvt_i32_f32_e32 v4, v4
	v_rndne_f32_e32 v11, v11
	v_rndne_f32_e32 v5, v5
	v_cvt_i32_f32_e32 v10, v10
	v_cvt_i32_f32_sdwa v11, v11 dst_sel:WORD_1 dst_unused:UNUSED_PAD src0_sel:DWORD
	v_cvt_i32_f32_e32 v5, v5
	v_lshlrev_b32_e32 v2, 8, v2
	v_and_b32_e32 v2, 0xff00, v2
	v_and_b32_e32 v9, 0xff0000, v9
	v_perm_b32 v3, v3, v8, s81
	v_or3_b32 v2, v3, v2, v9
	v_lshlrev_b32_e32 v3, 8, v4
	v_and_b32_e32 v3, 0xff00, v3
	v_and_b32_e32 v4, 0xff0000, v11
	v_perm_b32 v5, v5, v10, s81
	v_or3_b32 v3, v5, v3, v4
	v_add_co_u32_e32 v4, vcc, s44, v6
	s_nop 1
	v_addc_co_u32_e32 v5, vcc, 0, v7, vcc
	global_store_dwordx2 v[4:5], v[2:3], off
	v_lshl_add_u64 v[4:5], v[0:1], 0, s[2:3]
	ds_read_b128 v[0:3], v96 offset:12288
	s_waitcnt lgkmcnt(0)
; #define LAS __attribute__((address_space(3)))
; __device__ __forceinline__ float bflo(unsigned w) { return __uint_as_float(w << 16); }
; __device__ __forceinline__ float bfhi(unsigned w) { return __uint_as_float(w & 0xffff0000u); }
; __device__ __forceinline__ void direct_w8_block(const Ctx& c, LAS unsigned char* lds, const float* Wsrc, const int INC_, int srccol, unsigned char* dstrow, float* swdst) {
;     ...
; #pragma unroll
;     for (int t = 0; t < 8; ++t) { unsigned char* dt = dst + t * 64; asm volatile("" : "+v"(dt));
; #pragma unroll
;         for (int j = 0; j < 4; ++j) { v4u pk;
;             if (t < 4) { pk.x = held[t & 3][j][0]; pk.y = held[t & 3][j][1]; pk.z = held[t & 3][j][2]; pk.w = held[t & 3][j][3]; }
;             else pk = *(const LAS v4u*)(hl + ((t - 4) * 4 + j) * 1024);
;             int qi[8];
; #pragma unroll
;             for (int pr = 0; pr < 4; ++pr) { qi[2 * pr] = __float2int_rn(bflo(pk[pr]) * inv[j]); qi[2 * pr + 1] = __float2int_rn(bfhi(pk[pr]) * inv[j]); }
;             v2u w; w.x = (unsigned)(qi[0] & 255) | ((unsigned)(qi[1] & 255) << 8) | ((unsigned)(qi[2] & 255) << 16) | ((unsigned)(qi[3] & 255) << 24);
;             w.y = (unsigned)(qi[4] & 255) | ((unsigned)(qi[5] & 255) << 8) | ((unsigned)(qi[6] & 255) << 16) | ((unsigned)(qi[7] & 255) << 24);
;             *(v2u*)(dt + (size_t)j * DM) = w; } }
	v_lshlrev_b32_e32 v6, 16, v0
	v_and_b32_e32 v0, 0xffff0000, v0
	v_mul_f32_e32 v0, v135, v0
	v_lshlrev_b32_e32 v7, 16, v1
	v_and_b32_e32 v1, 0xffff0000, v1
	v_mul_f32_e32 v6, v135, v6
	v_rndne_f32_e32 v0, v0
	v_mul_f32_e32 v7, v135, v7
	v_mul_f32_e32 v1, v135, v1
	v_lshlrev_b32_e32 v8, 16, v2
	v_and_b32_e32 v2, 0xffff0000, v2
	v_rndne_f32_e32 v6, v6
	v_cvt_i32_f32_e32 v0, v0
	v_rndne_f32_e32 v7, v7
	v_rndne_f32_e32 v1, v1
	v_mul_f32_e32 v2, v135, v2
	v_lshlrev_b32_e32 v9, 16, v3
	v_and_b32_e32 v3, 0xffff0000, v3
	v_cvt_i32_f32_e32 v6, v6
	v_cvt_i32_f32_sdwa v7, v7 dst_sel:WORD_1 dst_unused:UNUSED_PAD src0_sel:DWORD
	v_cvt_i32_f32_e32 v1, v1
	v_mul_f32_e32 v8, v135, v8
	v_rndne_f32_e32 v2, v2
	v_mul_f32_e32 v9, v135, v9
	v_mul_f32_e32 v3, v135, v3
	v_rndne_f32_e32 v8, v8
	v_cvt_i32_f32_e32 v2, v2
	v_rndne_f32_e32 v9, v9
	v_rndne_f32_e32 v3, v3
	v_cvt_i32_f32_e32 v8, v8
	v_cvt_i32_f32_sdwa v9, v9 dst_sel:WORD_1 dst_unused:UNUSED_PAD src0_sel:DWORD
	v_cvt_i32_f32_e32 v3, v3
	v_lshlrev_b32_e32 v0, 8, v0
	v_and_b32_e32 v0, 0xff00, v0
	v_and_b32_e32 v7, 0xff0000, v7
	v_perm_b32 v1, v1, v6, s81
	v_or3_b32 v0, v1, v0, v7
	v_lshlrev_b32_e32 v1, 8, v2
	v_and_b32_e32 v1, 0xff00, v1
	v_and_b32_e32 v2, 0xff0000, v9
	v_perm_b32 v3, v3, v8, s81
	v_or3_b32 v1, v3, v1, v2
	global_store_dwordx2 v[4:5], v[0:1], off
	ds_read_b128 v[0:3], v96 offset:13312
	s_waitcnt lgkmcnt(0)
	v_lshlrev_b32_e32 v6, 16, v0
	v_and_b32_e32 v0, 0xffff0000, v0
	v_mul_f32_e32 v0, v134, v0
	v_lshlrev_b32_e32 v7, 16, v1
	v_and_b32_e32 v1, 0xffff0000, v1
	v_mul_f32_e32 v6, v134, v6
	v_rndne_f32_e32 v0, v0
	v_mul_f32_e32 v7, v134, v7
	v_mul_f32_e32 v1, v134, v1
	v_lshlrev_b32_e32 v8, 16, v2
	v_and_b32_e32 v2, 0xffff0000, v2
	v_rndne_f32_e32 v6, v6
	v_cvt_i32_f32_e32 v0, v0
	v_rndne_f32_e32 v7, v7
	v_rndne_f32_e32 v1, v1
	v_mul_f32_e32 v2, v134, v2
	v_lshlrev_b32_e32 v9, 16, v3
	v_and_b32_e32 v3, 0xffff0000, v3
	v_cvt_i32_f32_e32 v6, v6
	v_cvt_i32_f32_sdwa v7, v7 dst_sel:WORD_1 dst_unused:UNUSED_PAD src0_sel:DWORD
	v_cvt_i32_f32_e32 v1, v1
	v_mul_f32_e32 v8, v134, v8
	v_rndne_f32_e32 v2, v2
	v_mul_f32_e32 v9, v134, v9
	v_mul_f32_e32 v3, v134, v3
	v_rndne_f32_e32 v8, v8
	v_cvt_i32_f32_e32 v2, v2
	v_rndne_f32_e32 v9, v9
	v_rndne_f32_e32 v3, v3
	v_cvt_i32_f32_e32 v8, v8
	v_cvt_i32_f32_sdwa v9, v9 dst_sel:WORD_1 dst_unused:UNUSED_PAD src0_sel:DWORD
	v_cvt_i32_f32_e32 v3, v3
	v_lshlrev_b32_e32 v0, 8, v0
	v_and_b32_e32 v0, 0xff00, v0
	v_and_b32_e32 v7, 0xff0000, v7
	v_perm_b32 v1, v1, v6, s81
	v_or3_b32 v0, v1, v0, v7
	v_lshlrev_b32_e32 v1, 8, v2
	v_and_b32_e32 v1, 0xff00, v1
	v_and_b32_e32 v2, 0xff0000, v9
	v_perm_b32 v3, v3, v8, s81
	v_or3_b32 v1, v3, v1, v2
	v_add_co_u32_e32 v2, vcc, s67, v4
	s_nop 1
	v_addc_co_u32_e32 v3, vcc, 0, v5, vcc
	global_store_dwordx2 v[2:3], v[0:1], off
	ds_read_b128 v[0:3], v96 offset:14336
	s_waitcnt lgkmcnt(0)
	v_lshlrev_b32_e32 v6, 16, v0
	v_and_b32_e32 v0, 0xffff0000, v0
	v_mul_f32_e32 v0, v131, v0
	v_lshlrev_b32_e32 v7, 16, v1
	v_and_b32_e32 v1, 0xffff0000, v1
	v_mul_f32_e32 v6, v131, v6
	v_rndne_f32_e32 v0, v0
	v_mul_f32_e32 v7, v131, v7
	v_mul_f32_e32 v1, v131, v1
	v_lshlrev_b32_e32 v8, 16, v2
	v_and_b32_e32 v2, 0xffff0000, v2
	v_rndne_f32_e32 v6, v6
	v_cvt_i32_f32_e32 v0, v0
	v_rndne_f32_e32 v7, v7
	v_rndne_f32_e32 v1, v1
	v_mul_f32_e32 v2, v131, v2
	v_lshlrev_b32_e32 v9, 16, v3
	v_and_b32_e32 v3, 0xffff0000, v3
	v_cvt_i32_f32_e32 v6, v6
	v_cvt_i32_f32_sdwa v7, v7 dst_sel:WORD_1 dst_unused:UNUSED_PAD src0_sel:DWORD
	v_cvt_i32_f32_e32 v1, v1
	v_mul_f32_e32 v8, v131, v8
	v_rndne_f32_e32 v2, v2
	v_mul_f32_e32 v9, v131, v9
	v_mul_f32_e32 v3, v131, v3
	v_rndne_f32_e32 v8, v8
	v_cvt_i32_f32_e32 v2, v2
	v_rndne_f32_e32 v9, v9
	v_rndne_f32_e32 v3, v3
	v_cvt_i32_f32_e32 v8, v8
	v_cvt_i32_f32_sdwa v9, v9 dst_sel:WORD_1 dst_unused:UNUSED_PAD src0_sel:DWORD
	v_cvt_i32_f32_e32 v3, v3
	v_lshlrev_b32_e32 v0, 8, v0
	v_and_b32_e32 v0, 0xff00, v0
	v_and_b32_e32 v7, 0xff0000, v7
	v_perm_b32 v1, v1, v6, s81
	v_or3_b32 v0, v1, v0, v7
	v_lshlrev_b32_e32 v1, 8, v2
	v_and_b32_e32 v1, 0xff00, v1
	v_and_b32_e32 v2, 0xff0000, v9
	v_perm_b32 v3, v3, v8, s81
	v_or3_b32 v1, v3, v1, v2
	v_add_co_u32_e32 v2, vcc, s33, v4
	s_nop 1
	v_addc_co_u32_e32 v3, vcc, 0, v5, vcc
	global_store_dwordx2 v[2:3], v[0:1], off
	ds_read_b128 v[0:3], v96 offset:15360
	s_waitcnt lgkmcnt(0)
	v_lshlrev_b32_e32 v6, 16, v0
	v_and_b32_e32 v0, 0xffff0000, v0
	v_mul_f32_e32 v0, v130, v0
	v_lshlrev_b32_e32 v7, 16, v1
	v_and_b32_e32 v1, 0xffff0000, v1
	v_mul_f32_e32 v6, v130, v6
	v_rndne_f32_e32 v0, v0
	v_mul_f32_e32 v7, v130, v7
	v_mul_f32_e32 v1, v130, v1
	v_lshlrev_b32_e32 v8, 16, v2
	v_and_b32_e32 v2, 0xffff0000, v2
	v_rndne_f32_e32 v6, v6
	v_cvt_i32_f32_e32 v0, v0
	v_rndne_f32_e32 v7, v7
	v_rndne_f32_e32 v1, v1
	v_mul_f32_e32 v2, v130, v2
	v_lshlrev_b32_e32 v9, 16, v3
	v_and_b32_e32 v3, 0xffff0000, v3
	v_cvt_i32_f32_e32 v6, v6
	v_cvt_i32_f32_sdwa v7, v7 dst_sel:WORD_1 dst_unused:UNUSED_PAD src0_sel:DWORD
	v_cvt_i32_f32_e32 v1, v1
	v_mul_f32_e32 v8, v130, v8
	v_rndne_f32_e32 v2, v2
	v_mul_f32_e32 v9, v130, v9
	v_mul_f32_e32 v3, v130, v3
	v_rndne_f32_e32 v8, v8
	v_cvt_i32_f32_e32 v2, v2
	v_rndne_f32_e32 v9, v9
	v_rndne_f32_e32 v3, v3
	v_cvt_i32_f32_e32 v8, v8
	v_cvt_i32_f32_sdwa v9, v9 dst_sel:WORD_1 dst_unused:UNUSED_PAD src0_sel:DWORD
	v_cvt_i32_f32_e32 v3, v3
	v_lshlrev_b32_e32 v0, 8, v0
	v_and_b32_e32 v0, 0xff00, v0
	v_and_b32_e32 v7, 0xff0000, v7
	v_perm_b32 v1, v1, v6, s81
	v_or3_b32 v0, v1, v0, v7
	v_lshlrev_b32_e32 v1, 8, v2
	v_and_b32_e32 v1, 0xff00, v1
	v_and_b32_e32 v2, 0xff0000, v9
	v_perm_b32 v3, v3, v8, s81
	v_or3_b32 v1, v3, v1, v2
	v_add_co_u32_e32 v2, vcc, 0x3000, v4
	s_nop 1
	v_addc_co_u32_e32 v3, vcc, 0, v5, vcc
	global_store_dwordx2 v[2:3], v[0:1], off
	s_cbranch_scc1 .LBB0_457
